# rowwise phases: wave sums via DPP + permlane16/32 swaps instead of ds_bpermute chains; loop-invariant gain loads hoisted out of the row loop into v236-251
# speedup vs baseline: 1.0158x; 1.0106x over previous
; DI unsigned pack2(float a, float b) { f32v2_t v = {a, b}; return __builtin_bit_cast(unsigned, __builtin_convertvector(v, bf16v2_t)); }
; DI float wave_sum(float v) {
; #pragma unroll
;   for (int o = 32; o >= 1; o >>= 1) v += __shfl_xor(v, o);
;   return v;
; }
; __global__ void __launch_bounds__(256, 2) fwd_megakernel(Params p) {
;     ...
;         for (int u = 0; u < 2; u++) {
;           const int t = tb + u * stride2;
;           if (t < NT) {
;             float ss = 0.f;
; #pragma unroll
;             for (int j = 0; j < 4; j++) {
;               const float4 v = xv[u][j];
;               ss += v.x * v.x + v.y * v.y + v.z * v.z + v.w * v.w;
;               uint2 o; o.x = pack2(v.x, v.y); o.y = pack2(v.z, v.w);
;               *(uint2*)(xb0 + (long)t * 1024 + j * 256 + lane * 4) = o;
;             }
;             ss = wave_sum(ss);
;             if (lane == 0) rs[t] = rsqrtf(ss * (1.f / 1024.f) + EPS);
;           }
;         }
.LBB0_85:
	s_or_b64 exec, exec, s[12:13]
	s_waitcnt vmcnt(3)
	v_mul_f32_e32 v63, v31, v31
	s_waitcnt vmcnt(2)
	v_mul_f32_e32 v64, v27, v27
	v_fmac_f32_e32 v63, v30, v30
	v_fmac_f32_e32 v64, v26, v26
	v_fmac_f32_e32 v63, v32, v32
	v_fmac_f32_e32 v64, v28, v28
	v_fmac_f32_e32 v63, v33, v33
	v_fmac_f32_e32 v64, v29, v29
	v_add_f32_e32 v63, v63, v64
	s_waitcnt vmcnt(1)
	v_mul_f32_e32 v64, v23, v23
	v_fmac_f32_e32 v64, v22, v22
	v_fmac_f32_e32 v64, v24, v24
	v_fmac_f32_e32 v64, v25, v25
	v_add_f32_e32 v63, v63, v64
	s_waitcnt vmcnt(0)
	v_mul_f32_e32 v64, v19, v19
	v_fmac_f32_e32 v64, v18, v18
	v_fmac_f32_e32 v64, v20, v20
	v_fmac_f32_e32 v64, v21, v21
	v_add_f32_e32 v63, v63, v64
	s_nop 1
	v_add_f32_dpp v228, v63, v63 quad_perm:[1,0,3,2] row_mask:0xf bank_mask:0xf
	s_nop 1
	v_add_f32_dpp v228, v228, v228 quad_perm:[2,3,0,1] row_mask:0xf bank_mask:0xf
	s_nop 1
	v_add_f32_dpp v228, v228, v228 row_half_mirror row_mask:0xf bank_mask:0xf
	s_nop 1
	v_add_f32_dpp v228, v228, v228 row_mirror row_mask:0xf bank_mask:0xf
	s_nop 0
	v_mov_b32_e32 v255, v228
	s_nop 1
	v_permlane16_swap_b32_e32 v228, v255
	s_nop 0
	v_add_f32_e32 v228, v228, v255
	v_mov_b32_e32 v255, v228
	s_nop 1
	v_permlane32_swap_b32_e32 v228, v255
	s_nop 0
	v_add_f32_e32 v228, v228, v255
	v_cvt_pk_bf16_f32 v30, v30, v31
	v_cvt_pk_bf16_f32 v31, v32, v33
	v_cvt_pk_bf16_f32 v26, v26, v27
	v_cvt_pk_bf16_f32 v27, v28, v29
	s_waitcnt lgkmcnt(0)
	v_cvt_pk_bf16_f32 v18, v18, v19
	v_cvt_pk_bf16_f32 v19, v20, v21
	s_waitcnt lgkmcnt(0)
	v_lshlrev_b64 v[64:65], 11, v[50:51]
	v_lshl_add_u64 v[64:65], v[46:47], 0, v[64:65]
	global_store_dwordx2 v[64:65], v[30:31], off
	global_store_dwordx2 v[64:65], v[26:27], off offset:512
	s_waitcnt lgkmcnt(0)
	v_cvt_pk_bf16_f32 v26, v22, v23
	v_cvt_pk_bf16_f32 v27, v24, v25
	global_store_dwordx2 v[64:65], v[26:27], off offset:1024
	global_store_dwordx2 v[64:65], v[18:19], off offset:1536
	s_waitcnt lgkmcnt(0)
	s_waitcnt lgkmcnt(0)
	s_and_saveexec_b64 s[12:13], vcc
	s_cbranch_execz .LBB0_87
	s_waitcnt lgkmcnt(0)
	v_mov_b32_e32 v18, v228
	v_fmamk_f32 v18, v18, 0x3a800000, v43
	v_mul_f32_e32 v19, 0x4b800000, v18
	v_cmp_gt_f32_e64 s[10:11], s14, v18
	s_nop 1
	v_cndmask_b32_e64 v18, v18, v19, s[10:11]
	v_rsq_f32_e32 v18, v18
	s_nop 0
	v_mul_f32_e32 v19, 0x45800000, v18
	v_cndmask_b32_e64 v20, v18, v19, s[10:11]
	v_lshl_add_u64 v[18:19], v[50:51], 2, v[44:45]
	global_store_dword v[18:19], v20, off
.LBB0_87:
	s_or_b64 exec, exec, s[12:13]
	s_and_saveexec_b64 s[10:11], s[8:9]
	s_cbranch_execz .LBB0_82
	v_mul_f32_e32 v18, v3, v3
	v_mul_f32_e32 v19, v7, v7
	v_fmac_f32_e32 v18, v2, v2
	v_fmac_f32_e32 v19, v6, v6
	v_fmac_f32_e32 v18, v4, v4
	v_fmac_f32_e32 v19, v8, v8
	v_fmac_f32_e32 v18, v5, v5
	v_fmac_f32_e32 v19, v9, v9
	v_add_f32_e32 v18, v18, v19
	v_mul_f32_e32 v19, v11, v11
	v_fmac_f32_e32 v19, v10, v10
	v_fmac_f32_e32 v19, v12, v12
	v_fmac_f32_e32 v19, v13, v13
	v_add_f32_e32 v18, v18, v19
	v_mul_f32_e32 v19, v15, v15
	v_fmac_f32_e32 v19, v14, v14
	v_fmac_f32_e32 v19, v16, v16
	v_fmac_f32_e32 v19, v17, v17
	v_add_f32_e32 v18, v18, v19
	s_nop 1
	v_add_f32_dpp v229, v18, v18 quad_perm:[1,0,3,2] row_mask:0xf bank_mask:0xf
	s_nop 1
	v_add_f32_dpp v229, v229, v229 quad_perm:[2,3,0,1] row_mask:0xf bank_mask:0xf
	s_nop 1
	v_add_f32_dpp v229, v229, v229 row_half_mirror row_mask:0xf bank_mask:0xf
	s_nop 1
	v_add_f32_dpp v229, v229, v229 row_mirror row_mask:0xf bank_mask:0xf
	s_nop 0
	v_mov_b32_e32 v255, v229
	s_nop 1
	v_permlane16_swap_b32_e32 v229, v255
	s_nop 0
	v_add_f32_e32 v229, v229, v255
	v_mov_b32_e32 v255, v229
	s_nop 1
	v_permlane32_swap_b32_e32 v229, v255
	s_nop 0
	v_add_f32_e32 v229, v229, v255
	s_waitcnt lgkmcnt(0)
	s_waitcnt lgkmcnt(0)
	v_lshlrev_b64 v[18:19], 11, v[52:53]
	v_lshl_add_u64 v[20:21], v[46:47], 0, v[18:19]
	v_cvt_pk_bf16_f32 v18, v2, v3
	v_cvt_pk_bf16_f32 v19, v4, v5
	s_waitcnt lgkmcnt(0)
	global_store_dwordx2 v[20:21], v[18:19], off
	v_cvt_pk_bf16_f32 v18, v6, v7
	v_cvt_pk_bf16_f32 v19, v8, v9
	global_store_dwordx2 v[20:21], v[18:19], off offset:512
	s_waitcnt lgkmcnt(0)
	v_cvt_pk_bf16_f32 v22, v10, v11
	v_cvt_pk_bf16_f32 v23, v12, v13
	global_store_dwordx2 v[20:21], v[22:23], off offset:1024
	v_cvt_pk_bf16_f32 v22, v14, v15
	s_waitcnt lgkmcnt(0)
	v_cvt_pk_bf16_f32 v23, v16, v17
	global_store_dwordx2 v[20:21], v[22:23], off offset:1536
	s_and_b64 exec, exec, vcc
	s_cbranch_execz .LBB0_82
	s_waitcnt lgkmcnt(0)
	v_mov_b32_e32 v18, v229
	v_fmamk_f32 v18, v18, 0x3a800000, v43
	v_mul_f32_e32 v19, 0x4b800000, v18
	v_cmp_gt_f32_e64 s[8:9], s14, v18
	s_nop 1
	v_cndmask_b32_e64 v18, v18, v19, s[8:9]
	v_rsq_f32_e32 v18, v18
	s_nop 0
	v_mul_f32_e32 v19, 0x45800000, v18
	v_cndmask_b32_e64 v20, v18, v19, s[8:9]
	v_lshl_add_u64 v[18:19], v[52:53], 2, v[44:45]
	global_store_dword v[18:19], v20, off
	s_branch .LBB0_82

; DI unsigned pack2(float a, float b) { f32v2_t v = {a, b}; return __builtin_bit_cast(unsigned, __builtin_convertvector(v, bf16v2_t)); }
; DI float4 ld_nt4(const float* q) { const f32x4n v = __builtin_nontemporal_load((const f32x4n*)q); return make_float4(v.x, v.y, v.z, v.w); }
; DI float wave_sum(float v) {
; #pragma unroll
;   for (int o = 32; o >= 1; o >>= 1) v += __shfl_xor(v, o);
;   return v;
; }
; __global__ void __launch_bounds__(256, 2) fwd_megakernel(Params p) {
;     ...
;     for (int t = blockIdx.x * 4 + wv; t < 256; t += gridDim.x * 4) {
;       const float* xr = p.in[I_MEMP] + (long)t * 1024;
;       float ss = 0.f;
; #pragma unroll
;       for (int j = 0; j < 4; j++) {
;         const float4 v = ld_nt4(xr + j * 256 + lane * 4);
;         ss += v.x * v.x + v.y * v.y + v.z * v.z + v.w * v.w;
;         uint2 o; o.x = pack2(v.x, v.y); o.y = pack2(v.z, v.w);
;         *(uint2*)(memb + (long)t * 1024 + j * 256 + lane * 4) = o;
;       }
;       ss = wave_sum(ss);
;       if (lane == 0) rsmem[t] = rsqrtf(ss * (1.f / 1024.f) + EPS);
;     }
.LBB0_93:
	v_ashrrev_i32_e32 v41, 31, v40
	s_waitcnt lgkmcnt(0)
	v_lshlrev_b64 v[14:15], 12, v[40:41]
	v_lshl_add_u64 v[26:27], v[4:5], 0, v[14:15]
	global_load_dwordx4 v[14:17], v[26:27], off nt
	v_lshlrev_b64 v[18:19], 11, v[40:41]
	v_lshl_add_u64 v[30:31], v[6:7], 0, v[18:19]
	s_waitcnt vmcnt(0)
	v_cvt_pk_bf16_f32 v18, v14, v15
	v_cvt_pk_bf16_f32 v19, v16, v17
	global_store_dwordx2 v[30:31], v[18:19], off
	global_load_dwordx4 v[18:21], v[26:27], off offset:1024 nt
	v_mul_f32_e32 v15, v15, v15
	v_fmac_f32_e32 v15, v14, v14
	v_fmac_f32_e32 v15, v16, v16
	v_fmac_f32_e32 v15, v17, v17
	s_waitcnt vmcnt(0)
	v_cvt_pk_bf16_f32 v22, v18, v19
	v_cvt_pk_bf16_f32 v23, v20, v21
	global_store_dwordx2 v[30:31], v[22:23], off offset:512
	global_load_dwordx4 v[22:25], v[26:27], off offset:2048 nt
	v_mul_f32_e32 v14, v19, v19
	v_fmac_f32_e32 v14, v18, v18
	v_fmac_f32_e32 v14, v20, v20
	v_fmac_f32_e32 v14, v21, v21
	v_add_f32_e32 v14, v15, v14
	s_waitcnt vmcnt(0)
	v_cvt_pk_bf16_f32 v28, v22, v23
	v_cvt_pk_bf16_f32 v29, v24, v25
	global_store_dwordx2 v[30:31], v[28:29], off offset:1024
	global_load_dwordx4 v[26:29], v[26:27], off offset:3072 nt
	v_mul_f32_e32 v15, v23, v23
	v_fmac_f32_e32 v15, v22, v22
	v_fmac_f32_e32 v15, v24, v24
	v_fmac_f32_e32 v15, v25, v25
	v_add_f32_e32 v14, v14, v15
	s_waitcnt vmcnt(0)
	v_mul_f32_e32 v15, v27, v27
	v_fmac_f32_e32 v15, v26, v26
	v_fmac_f32_e32 v15, v28, v28
	v_fmac_f32_e32 v15, v29, v29
	v_add_f32_e32 v14, v14, v15
	s_nop 1
	v_add_f32_dpp v230, v14, v14 quad_perm:[1,0,3,2] row_mask:0xf bank_mask:0xf
	s_nop 1
	v_add_f32_dpp v230, v230, v230 quad_perm:[2,3,0,1] row_mask:0xf bank_mask:0xf
	s_nop 1
	v_add_f32_dpp v230, v230, v230 row_half_mirror row_mask:0xf bank_mask:0xf
	s_nop 1
	v_add_f32_dpp v230, v230, v230 row_mirror row_mask:0xf bank_mask:0xf
	s_nop 0
	v_mov_b32_e32 v255, v230
	s_nop 1
	v_permlane16_swap_b32_e32 v230, v255
	s_nop 0
	v_add_f32_e32 v230, v230, v255
	v_mov_b32_e32 v255, v230
	s_nop 1
	v_permlane32_swap_b32_e32 v230, v255
	s_nop 0
	v_add_f32_e32 v230, v230, v255
	v_cvt_pk_bf16_f32 v16, v26, v27
	v_cvt_pk_bf16_f32 v17, v28, v29
	global_store_dwordx2 v[30:31], v[16:17], off offset:1536
	s_waitcnt lgkmcnt(0)
	s_waitcnt lgkmcnt(0)
	s_waitcnt lgkmcnt(0)
	s_waitcnt lgkmcnt(0)
	s_waitcnt lgkmcnt(0)
	s_and_saveexec_b64 s[10:11], vcc
	s_cbranch_execz .LBB0_92
	s_waitcnt lgkmcnt(0)
	v_mov_b32_e32 v14, v230
	v_fmamk_f32 v14, v14, 0x3a800000, v1
	v_mul_f32_e32 v15, 0x4b800000, v14
	v_cmp_gt_f32_e64 s[8:9], s12, v14
	s_nop 1
	v_cndmask_b32_e64 v14, v14, v15, s[8:9]
	v_rsq_f32_e32 v14, v14
	s_nop 0
	v_mul_f32_e32 v15, 0x45800000, v14
	v_cndmask_b32_e64 v16, v14, v15, s[8:9]
	v_lshl_add_u64 v[14:15], v[40:41], 2, v[2:3]
	global_store_dword v[14:15], v16, off
	s_branch .LBB0_92

; DI float bf2f(u16 h) { return __uint_as_float(((unsigned)h) << 16); }
; DI uint2 ld_nt2u(const void* q) { const u32x2n v = __builtin_nontemporal_load((const u32x2n*)q); return make_uint2(v.x, v.y); }
; DI int opaque_tid() { int t = threadIdx.x; asm volatile("" : "+v"(t)); return t; }
; DI u16* xres_base(const Params& p) { return (u16*)(p.out + O_Y) + 1024; }
; DI void rowwise_residual(const Params& p, const u16* Y, const float* gpost, int mode, const u16* parts) {
;   const int tid = opaque_tid(), lane = tid & 63, w = tid >> 6;
;   float* y = p.out + O_Y;
;   u16* xr = xres_base(p);
;   float* rs = (float*)(p.ws + W_RS);
;   const int stride = gridDim.x * 4;
;   for (int tb = blockIdx.x * 4 + w; tb < NT; tb += 2 * stride) {
;     float4 yv[2][4], xv[2][4];
;     float ss[2] = {0.f, 0.f};
; #pragma unroll
;     for (int u = 0; u < 2; u++) {
;       const int t = tb + u * stride;
;       if (t < NT) {
; #pragma unroll
;         for (int j = 0; j < 4; j++) {
;           const uint2 yr = ld_nt2u(Y + (long)t * 1024 + j * 256 + lane * 4);
;           yv[u][j] = make_float4(bf2f((u16)(yr.x & 0xffff)), bf2f((u16)(yr.x >> 16)), bf2f((u16)(yr.y & 0xffff)), bf2f((u16)(yr.y >> 16)));
;           if (mode == 0) xv[u][j] = *(const float4*)(xrow(p, t) + j * 256 + lane * 4);
;     ...
;           const float4 g = *(const float4*)(gpost + j * 256 + lane * 4);
.LBB0_901:
	s_or_b64 exec, exec, s[0:1]
	v_mov_b32_e32 v2, v202
	s_waitcnt lgkmcnt(0)
	s_barrier
	s_movk_i32 s26, 0x4800
	v_ashrrev_i32_e32 v0, 6, v2
	v_add_u32_e32 v32, s65, v0
	v_cmp_gt_i32_e32 vcc, s26, v32
	v_mov_b64_e32 v[0:1], s[48:49]
	s_and_saveexec_b64 s[0:1], vcc
	s_cbranch_execz .LBB0_916
	v_and_b32_e32 v1, 63, v2
	v_mov_b32_e32 v35, 0
	v_lshlrev_b32_e32 v36, 3, v1
	v_mov_b32_e32 v37, v35
	v_lshl_add_u64 v[2:3], s[48:49], 0, v[36:37]
	s_mov_b64 s[8:9], 0x6900000
	v_lshl_add_u64 v[38:39], v[2:3], 0, s[8:9]
	s_mov_b64 s[8:9], 0xb100000
	v_lshl_add_u64 v[42:43], v[2:3], 0, s[8:9]
	v_and_b32_e32 v2, 64, v203
	v_add_u32_e32 v2, 64, v2
	v_xor_b32_e32 v3, 32, v203
	v_cmp_lt_i32_e64 s[8:9], v3, v2
	s_load_dwordx2 s[12:13], s[62:63], 0xd8
	s_load_dwordx2 s[2:3], s[62:63], 0x48
	s_load_dwordx4 s[28:31], s[62:63], 0x0
	v_cndmask_b32_e64 v3, v203, v3, s[8:9]
	v_lshlrev_b32_e32 v92, 2, v3
	v_xor_b32_e32 v3, 16, v203
	v_cmp_lt_i32_e64 s[8:9], v3, v2
	v_ashrrev_i32_e32 v33, 31, v32
	s_mov_b64 s[10:11], 0x10000
	v_cndmask_b32_e64 v3, v203, v3, s[8:9]
	v_lshlrev_b32_e32 v93, 2, v3
	v_xor_b32_e32 v3, 8, v203
	v_cmp_lt_i32_e64 s[8:9], v3, v2
	s_add_u32 s14, s48, 0x10000
	s_addc_u32 s15, s49, 0
	v_cndmask_b32_e64 v3, v203, v3, s[8:9]
	v_lshlrev_b32_e32 v94, 2, v3
	v_xor_b32_e32 v3, 4, v203
	v_cmp_lt_i32_e64 s[8:9], v3, v2
	s_lshl_b32 s16, s50, 3
	v_lshlrev_b32_e32 v0, 2, v1
	v_cndmask_b32_e64 v3, v203, v3, s[8:9]
	v_lshlrev_b32_e32 v95, 2, v3
	v_xor_b32_e32 v3, 2, v203
	v_cmp_lt_i32_e64 s[8:9], v3, v2
	v_lshlrev_b32_e32 v34, 4, v1
	s_ashr_i32 s17, s16, 31
	v_cndmask_b32_e64 v3, v203, v3, s[8:9]
	v_lshlrev_b32_e32 v96, 2, v3
	v_xor_b32_e32 v3, 1, v203
	v_cmp_lt_i32_e64 s[8:9], v3, v2
	s_waitcnt lgkmcnt(0)
	v_lshl_add_u64 v[40:41], s[12:13], 0, v[36:37]
	v_cmp_lt_u32_e32 vcc, 31, v1
	v_cndmask_b32_e64 v2, v203, v3, s[8:9]
	v_lshlrev_b32_e32 v97, 2, v2
	v_lshl_add_u64 v[2:3], v[32:33], 2, s[48:49]
	v_lshl_add_u64 v[46:47], v[2:3], 0, s[10:11]
	v_lshlrev_b64 v[2:3], 12, v[32:33]
	v_lshl_add_u64 v[48:49], s[12:13], 0, v[2:3]
	v_lshlrev_b64 v[2:3], 11, v[32:33]
	v_lshl_add_u64 v[44:45], s[2:3], 0, v[34:35]
	global_load_dwordx4 v[236:239], v[44:45], off
	global_load_dwordx4 v[240:243], v[44:45], off offset:1024
	global_load_dwordx4 v[244:247], v[44:45], off offset:2048
	global_load_dwordx4 v[248:251], v[44:45], off offset:3072
	s_waitcnt vmcnt(0)
	v_cmp_eq_u32_e64 s[8:9], 0, v1
	s_lshl_b64 s[18:19], s[16:17], 2
	s_lshl_b64 s[20:21], s[16:17], 12
	v_lshl_add_u64 v[50:51], s[48:49], 0, v[2:3]
	s_lshl_b64 s[24:25], s[16:17], 11
	s_mov_b64 s[22:23], 0
	s_movk_i32 s27, 0x4000
	v_mov_b32_e32 v98, s31
	v_mov_b32_e32 v99, s29
	v_mov_b32_e32 v100, s30
	v_mov_b32_e32 v101, s28
	v_lshlrev_b32_e32 v52, 2, v0
	v_mov_b32_e32 v53, v35
	s_mov_b32 s28, 0x6900000
	s_movk_i32 s29, 0x7ff
	v_mov_b32_e32 v102, 0x358637bd
	s_mov_b32 s30, 0x800000
	s_movk_i32 s31, 0x47ff
	s_branch .LBB0_904

; DI unsigned pack2(float a, float b) { f32v2_t v = {a, b}; return __builtin_bit_cast(unsigned, __builtin_convertvector(v, bf16v2_t)); }
; DI void st_nt4(float* q, float4 v) { f32x4n t = {v.x, v.y, v.z, v.w}; __builtin_nontemporal_store(t, (f32x4n*)q); }
; DI void rowwise_residual(const Params& p, const u16* Y, const float* gpost, int mode, const u16* parts) {
;     ...
;     ss[0] = wave_sum(ss[0]); ss[1] = wave_sum(ss[1]);
; #pragma unroll
;     for (int u = 0; u < 2; u++) {
;       const int t = tb + u * stride;
;       if (t < NT) {
;         const float r = rsqrtf(ss[u] * (1.f / 1024.f) + EPS);
;         float s2 = 0.f;
; #pragma unroll
;         for (int j = 0; j < 4; j++) {
;           const float4 g = *(const float4*)(gpost + j * 256 + lane * 4);
;           float4 xn = xv[u][j];
;           xn.x += yv[u][j].x * r * g.x; xn.y += yv[u][j].y * r * g.y; xn.z += yv[u][j].z * r * g.z; xn.w += yv[u][j].w * r * g.w;
;           s2 += xn.x * xn.x + xn.y * xn.y + xn.z * xn.z + xn.w * xn.w;
;           if (mode == 2) st_nt4(y + (long)t * 1024 + j * 256 + lane * 4, xn);
;           else {
;             uint2 o; o.x = pack2(xn.x, xn.y); o.y = pack2(xn.z, xn.w);
;             *(uint2*)(xr + (long)t * XR_LD + j * 256 + lane * 4) = o;
;           }
;         }
;         if (mode != 2) {
;           s2 = wave_sum(s2);
;           if (lane == 0) rs[t] = rsqrtf(s2 * (1.f / 1024.f) + EPS);
;         }
.LBB0_910:
	s_or_b64 exec, exec, s[2:3]
	s_nop 1
	v_mov_b32_e32 v104, v236
	v_mov_b32_e32 v105, v237
	v_mov_b32_e32 v106, v238
	v_mov_b32_e32 v107, v239
	s_nop 1
	v_add_f32_dpp v231, v88, v88 quad_perm:[1,0,3,2] row_mask:0xf bank_mask:0xf
	s_nop 1
	v_add_f32_dpp v231, v231, v231 quad_perm:[2,3,0,1] row_mask:0xf bank_mask:0xf
	s_nop 1
	v_add_f32_dpp v231, v231, v231 row_half_mirror row_mask:0xf bank_mask:0xf
	s_nop 1
	v_add_f32_dpp v231, v231, v231 row_mirror row_mask:0xf bank_mask:0xf
	s_nop 0
	v_mov_b32_e32 v255, v231
	s_nop 1
	v_permlane16_swap_b32_e32 v231, v255
	s_nop 0
	v_add_f32_e32 v231, v231, v255
	v_mov_b32_e32 v255, v231
	s_nop 1
	v_permlane32_swap_b32_e32 v231, v255
	s_nop 0
	v_add_f32_e32 v231, v231, v255
	v_mov_b32_e32 v108, v82
	v_mov_b32_e32 v109, v80
	v_mov_b32_e32 v110, v84
	v_mov_b32_e32 v111, v86
	s_waitcnt lgkmcnt(0)
	v_mov_b32_e32 v86, v85
	s_waitcnt lgkmcnt(0)
	s_waitcnt lgkmcnt(0)
	s_waitcnt lgkmcnt(0)
	s_waitcnt lgkmcnt(0)
	v_lshl_add_u64 v[88:89], v[48:49], 0, v[36:37]
	s_waitcnt lgkmcnt(0)
	v_mov_b32_e32 v34, v231
	v_fmamk_f32 v34, v34, 0x3a800000, v102
	v_mul_f32_e32 v82, 0x4b800000, v34
	v_cmp_gt_f32_e64 s[12:13], s30, v34
	s_nop 1
	v_cndmask_b32_e64 v34, v34, v82, s[12:13]
	v_rsq_f32_e32 v34, v34
	s_nop 0
	v_mul_f32_e32 v80, 0x45800000, v34
	v_cndmask_b32_e64 v34, v34, v80, s[12:13]
	v_pk_mul_f32 v[108:109], v[34:35], v[108:109] op_sel_hi:[0,1]
	v_pk_mul_f32 v[110:111], v[34:35], v[110:111] op_sel_hi:[0,1]
	v_mov_b32_e32 v80, v83
	v_pk_mul_f32 v[80:81], v[34:35], v[80:81] op_sel_hi:[0,1]
	v_pk_mul_f32 v[82:83], v[34:35], v[86:87] op_sel_hi:[0,1]
	v_pk_mul_f32 v[76:77], v[34:35], v[76:77] op_sel_hi:[0,1]
	v_pk_mul_f32 v[78:79], v[34:35], v[78:79] op_sel_hi:[0,1]
	v_pk_mul_f32 v[74:75], v[74:75], v[34:35] op_sel_hi:[1,0]
	v_pk_mul_f32 v[72:73], v[72:73], v[34:35] op_sel_hi:[1,0]
	s_waitcnt vmcnt(0)
	v_pk_fma_f32 v[104:105], v[104:105], v[108:109], v[28:29]
	v_pk_fma_f32 v[106:107], v[106:107], v[110:111], v[30:31]
	v_cvt_pk_bf16_f32 v28, v104, v105
	v_cvt_pk_bf16_f32 v29, v106, v107
	global_store_dwordx2 v[88:89], v[28:29], off offset:2048
	s_nop 1
	v_mov_b32_e32 v28, v240
	v_mov_b32_e32 v29, v241
	v_mov_b32_e32 v30, v242
	v_mov_b32_e32 v31, v243
	v_pk_fma_f32 v[28:29], v[80:81], v[28:29], v[24:25]
	v_pk_fma_f32 v[30:31], v[82:83], v[30:31], v[26:27]
	v_cvt_pk_bf16_f32 v24, v28, v29
	v_cvt_pk_bf16_f32 v25, v30, v31
	global_store_dwordx2 v[88:89], v[24:25], off offset:2560
	s_nop 1
	v_mov_b32_e32 v24, v244
	v_mov_b32_e32 v25, v245
	v_mov_b32_e32 v26, v246
	v_mov_b32_e32 v27, v247
	v_pk_mul_f32 v[28:29], v[28:29], v[28:29]
	v_pk_mul_f32 v[30:31], v[30:31], v[30:31]
	v_add_f32_e32 v28, v28, v29
	v_add_f32_e32 v28, v28, v30
	v_add_f32_e32 v28, v28, v31
	s_nop 1
	v_add_f32_dpp v233, v91, v91 quad_perm:[1,0,3,2] row_mask:0xf bank_mask:0xf
	s_nop 1
	v_add_f32_dpp v233, v233, v233 quad_perm:[2,3,0,1] row_mask:0xf bank_mask:0xf
	s_nop 1
	v_add_f32_dpp v233, v233, v233 row_half_mirror row_mask:0xf bank_mask:0xf
	s_nop 1
	v_add_f32_dpp v233, v233, v233 row_mirror row_mask:0xf bank_mask:0xf
	s_nop 0
	v_mov_b32_e32 v255, v233
	s_nop 1
	v_permlane16_swap_b32_e32 v233, v255
	s_nop 0
	v_add_f32_e32 v233, v233, v255
	v_mov_b32_e32 v255, v233
	s_nop 1
	v_permlane32_swap_b32_e32 v233, v255
	s_nop 0
	v_add_f32_e32 v233, v233, v255
	v_pk_fma_f32 v[24:25], v[76:77], v[24:25], v[20:21]
	v_pk_fma_f32 v[26:27], v[78:79], v[26:27], v[22:23]
	v_cvt_pk_bf16_f32 v20, v24, v25
	v_cvt_pk_bf16_f32 v21, v26, v27
	global_store_dwordx2 v[88:89], v[20:21], off offset:3072
	s_nop 1
	v_mov_b32_e32 v20, v248
	v_mov_b32_e32 v21, v249
	v_mov_b32_e32 v22, v250
	v_mov_b32_e32 v23, v251
	v_pk_mul_f32 v[76:77], v[104:105], v[104:105]
	v_pk_mul_f32 v[78:79], v[106:107], v[106:107]
	v_add_f32_e32 v34, v76, v77
	v_pk_mul_f32 v[24:25], v[24:25], v[24:25]
	v_add_f32_e32 v34, v78, v34
	v_pk_mul_f32 v[26:27], v[26:27], v[26:27]
	v_add_f32_e32 v24, v24, v25
	v_add_f32_e32 v34, v79, v34
	v_add_f32_e32 v24, v24, v26
	v_add_f32_e32 v28, v34, v28
	v_add_f32_e32 v24, v24, v27
	v_add_f32_e32 v24, v28, v24
	v_pk_fma_f32 v[20:21], v[74:75], v[20:21], v[16:17]
	v_pk_fma_f32 v[22:23], v[72:73], v[22:23], v[18:19]
	v_pk_mul_f32 v[16:17], v[20:21], v[20:21]
	v_pk_mul_f32 v[18:19], v[22:23], v[22:23]
	v_add_f32_e32 v16, v16, v17
	v_add_f32_e32 v16, v16, v18
	v_add_f32_e32 v16, v16, v19
	v_add_f32_e32 v16, v24, v16
	s_nop 1
	v_add_f32_dpp v232, v16, v16 quad_perm:[1,0,3,2] row_mask:0xf bank_mask:0xf
	s_nop 1
	v_add_f32_dpp v232, v232, v232 quad_perm:[2,3,0,1] row_mask:0xf bank_mask:0xf
	s_nop 1
	v_add_f32_dpp v232, v232, v232 row_half_mirror row_mask:0xf bank_mask:0xf
	s_nop 1
	v_add_f32_dpp v232, v232, v232 row_mirror row_mask:0xf bank_mask:0xf
	s_nop 0
	v_mov_b32_e32 v255, v232
	s_nop 1
	v_permlane16_swap_b32_e32 v232, v255
	s_nop 0
	v_add_f32_e32 v232, v232, v255
	v_mov_b32_e32 v255, v232
	s_nop 1
	v_permlane32_swap_b32_e32 v232, v255
	s_nop 0
	v_add_f32_e32 v232, v232, v255
	s_waitcnt lgkmcnt(1)
	v_cvt_pk_bf16_f32 v20, v20, v21
	v_cvt_pk_bf16_f32 v21, v22, v23
	s_waitcnt lgkmcnt(1)
	s_waitcnt lgkmcnt(1)
	global_store_dwordx2 v[88:89], v[20:21], off offset:3584
	s_waitcnt lgkmcnt(1)
	s_waitcnt lgkmcnt(1)
	s_waitcnt lgkmcnt(1)
	s_waitcnt lgkmcnt(1)
	s_waitcnt lgkmcnt(1)
	s_waitcnt lgkmcnt(1)
	s_waitcnt lgkmcnt(1)
	s_and_saveexec_b64 s[2:3], s[8:9]
	s_cbranch_execz .LBB0_912
	s_waitcnt lgkmcnt(0)
	v_mov_b32_e32 v18, v232
	v_fmamk_f32 v18, v18, 0x3a800000, v102
	v_mul_f32_e32 v19, 0x4b800000, v18
	v_cmp_gt_f32_e64 s[12:13], s30, v18
	s_nop 1
	v_cndmask_b32_e64 v18, v18, v19, s[12:13]
	v_rsq_f32_e32 v18, v18
	s_nop 0
	v_mul_f32_e32 v19, 0x45800000, v18
	v_cndmask_b32_e64 v18, v18, v19, s[12:13]
	global_store_dword v[46:47], v18, off
; DI unsigned pack2(float a, float b) { f32v2_t v = {a, b}; return __builtin_bit_cast(unsigned, __builtin_convertvector(v, bf16v2_t)); }
; DI void st_nt4(float* q, float4 v) { f32x4n t = {v.x, v.y, v.z, v.w}; __builtin_nontemporal_store(t, (f32x4n*)q); }
; DI void rowwise_residual(const Params& p, const u16* Y, const float* gpost, int mode, const u16* parts) {
;     ...
;     for (int u = 0; u < 2; u++) {
;       const int t = tb + u * stride;
;       if (t < NT) {
;         const float r = rsqrtf(ss[u] * (1.f / 1024.f) + EPS);
;         float s2 = 0.f;
; #pragma unroll
;         for (int j = 0; j < 4; j++) {
;           const float4 g = *(const float4*)(gpost + j * 256 + lane * 4);
;           float4 xn = xv[u][j];
;           xn.x += yv[u][j].x * r * g.x; xn.y += yv[u][j].y * r * g.y; xn.z += yv[u][j].z * r * g.z; xn.w += yv[u][j].w * r * g.w;
;           s2 += xn.x * xn.x + xn.y * xn.y + xn.z * xn.z + xn.w * xn.w;
;           if (mode == 2) st_nt4(y + (long)t * 1024 + j * 256 + lane * 4, xn);
;           else {
;             uint2 o; o.x = pack2(xn.x, xn.y); o.y = pack2(xn.z, xn.w);
;             *(uint2*)(xr + (long)t * XR_LD + j * 256 + lane * 4) = o;
;           }
;         }
;         if (mode != 2) {
;           s2 = wave_sum(s2);
;           if (lane == 0) rs[t] = rsqrtf(s2 * (1.f / 1024.f) + EPS);
;         }
.LBB0_912:
	s_or_b64 exec, exec, s[2:3]
	s_and_saveexec_b64 s[2:3], s[10:11]
	s_cbranch_execz .LBB0_903
	s_waitcnt lgkmcnt(0)
	s_nop 1
	v_mov_b32_e32 v18, v236
	v_mov_b32_e32 v19, v237
	v_mov_b32_e32 v20, v238
	v_mov_b32_e32 v21, v239
	v_mov_b32_e32 v16, v233
	v_fmamk_f32 v16, v16, 0x3a800000, v102
	v_mul_f32_e32 v17, 0x4b800000, v16
	v_cmp_gt_f32_e64 s[10:11], s30, v16
	s_nop 1
	v_cndmask_b32_e64 v16, v16, v17, s[10:11]
	v_rsq_f32_e32 v24, v16
	v_lshlrev_b64 v[16:17], 12, v[70:71]
	v_lshl_add_u64 v[22:23], v[40:41], 0, v[16:17]
	v_mul_f32_e32 v16, 0x45800000, v24
	v_cndmask_b32_e64 v24, v24, v16, s[10:11]
	v_pk_mul_f32 v[16:17], v[58:59], v[24:25] op_sel_hi:[1,0]
	v_pk_mul_f32 v[26:27], v[60:61], v[24:25] op_sel_hi:[1,0]
	v_pk_mul_f32 v[30:31], v[64:65], v[24:25] op_sel_hi:[1,0]
	v_pk_mul_f32 v[72:73], v[66:67], v[24:25] op_sel_hi:[1,0]
	v_pk_mul_f32 v[74:75], v[68:69], v[24:25] op_sel_hi:[1,0]
	v_pk_mul_f32 v[76:77], v[56:57], v[24:25] op_sel_hi:[1,0]
	v_pk_fma_f32 v[28:29], v[16:17], v[18:19], v[0:1]
	v_pk_fma_f32 v[20:21], v[26:27], v[20:21], v[2:3]
	v_cvt_pk_bf16_f32 v16, v28, v29
	v_cvt_pk_bf16_f32 v17, v20, v21
	global_store_dwordx2 v[22:23], v[16:17], off offset:2048
	s_nop 1
	v_mov_b32_e32 v16, v240
	v_mov_b32_e32 v17, v241
	v_mov_b32_e32 v18, v242
	v_mov_b32_e32 v19, v243
	v_pk_mul_f32 v[26:27], v[62:63], v[24:25] op_sel_hi:[1,0]
	v_pk_mul_f32 v[28:29], v[28:29], v[28:29]
	v_pk_mul_f32 v[20:21], v[20:21], v[20:21]
	v_add_f32_e32 v28, v28, v29
	v_add_f32_e32 v20, v28, v20
	v_add_f32_e32 v28, v20, v21
	v_pk_mul_f32 v[24:25], v[54:55], v[24:25] op_sel_hi:[1,0]
	v_pk_fma_f32 v[26:27], v[26:27], v[16:17], v[4:5]
	v_pk_fma_f32 v[30:31], v[30:31], v[18:19], v[6:7]
	v_cvt_pk_bf16_f32 v16, v26, v27
	v_cvt_pk_bf16_f32 v17, v30, v31
	global_store_dwordx2 v[22:23], v[16:17], off offset:2560
	s_nop 1
	v_mov_b32_e32 v16, v244
	v_mov_b32_e32 v17, v245
	v_mov_b32_e32 v18, v246
	v_mov_b32_e32 v19, v247
	v_pk_mul_f32 v[20:21], v[26:27], v[26:27]
	v_pk_mul_f32 v[26:27], v[30:31], v[30:31]
	v_add_f32_e32 v20, v20, v21
	v_add_f32_e32 v20, v20, v26
	v_add_f32_e32 v20, v20, v27
	v_add_f32_e32 v28, v28, v20
	v_pk_fma_f32 v[72:73], v[72:73], v[16:17], v[8:9]
	v_pk_fma_f32 v[74:75], v[74:75], v[18:19], v[10:11]
	v_cvt_pk_bf16_f32 v16, v72, v73
	v_cvt_pk_bf16_f32 v17, v74, v75
	global_store_dwordx2 v[22:23], v[16:17], off offset:3072
	s_nop 1
	v_mov_b32_e32 v16, v248
	v_mov_b32_e32 v17, v249
	v_mov_b32_e32 v18, v250
	v_mov_b32_e32 v19, v251
	v_pk_mul_f32 v[20:21], v[72:73], v[72:73]
	v_pk_mul_f32 v[26:27], v[74:75], v[74:75]
	v_add_f32_e32 v20, v20, v21
	v_add_f32_e32 v20, v20, v26
	v_add_f32_e32 v26, v20, v27
	v_add_f32_e32 v26, v28, v26
	v_pk_fma_f32 v[20:21], v[76:77], v[16:17], v[12:13]
	v_pk_fma_f32 v[18:19], v[24:25], v[18:19], v[14:15]
	v_pk_mul_f32 v[16:17], v[20:21], v[20:21]
	v_pk_mul_f32 v[24:25], v[18:19], v[18:19]
	v_add_f32_e32 v16, v16, v17
	v_add_f32_e32 v16, v16, v24
	v_add_f32_e32 v16, v16, v25
	v_add_f32_e32 v16, v26, v16
	s_nop 1
	v_add_f32_dpp v234, v16, v16 quad_perm:[1,0,3,2] row_mask:0xf bank_mask:0xf
	s_nop 1
	v_add_f32_dpp v234, v234, v234 quad_perm:[2,3,0,1] row_mask:0xf bank_mask:0xf
	s_nop 1
	v_add_f32_dpp v234, v234, v234 row_half_mirror row_mask:0xf bank_mask:0xf
	s_nop 1
	v_add_f32_dpp v234, v234, v234 row_mirror row_mask:0xf bank_mask:0xf
	s_nop 0
	v_mov_b32_e32 v255, v234
	s_nop 1
	v_permlane16_swap_b32_e32 v234, v255
	s_nop 0
	v_add_f32_e32 v234, v234, v255
	v_mov_b32_e32 v255, v234
	s_nop 1
	v_permlane32_swap_b32_e32 v234, v255
	s_nop 0
	v_add_f32_e32 v234, v234, v255
	v_cvt_pk_bf16_f32 v20, v20, v21
	v_cvt_pk_bf16_f32 v21, v18, v19
	global_store_dwordx2 v[22:23], v[20:21], off offset:3584
	s_waitcnt lgkmcnt(0)
	s_waitcnt lgkmcnt(0)
	s_waitcnt lgkmcnt(0)
	s_waitcnt lgkmcnt(0)
	s_waitcnt lgkmcnt(0)
	s_and_b64 exec, exec, s[8:9]
	s_cbranch_execz .LBB0_903
	s_waitcnt lgkmcnt(0)
	v_mov_b32_e32 v16, v234
	v_fmamk_f32 v16, v16, 0x3a800000, v102
	v_mul_f32_e32 v17, 0x4b800000, v16
	v_cmp_gt_f32_e64 s[10:11], s30, v16
	s_nop 1
	v_cndmask_b32_e64 v16, v16, v17, s[10:11]
	v_rsq_f32_e32 v16, v16
	s_nop 0
	v_mul_f32_e32 v17, 0x45800000, v16
	v_cndmask_b32_e64 v18, v16, v17, s[10:11]
	v_lshl_add_u64 v[16:17], v[70:71], 2, s[14:15]
	global_store_dword v[16:17], v18, off
	s_branch .LBB0_903

; DI float bf2f(u16 h) { return __uint_as_float(((unsigned)h) << 16); }
; DI uint2 ld_nt2u(const void* q) { const u32x2n v = __builtin_nontemporal_load((const u32x2n*)q); return make_uint2(v.x, v.y); }
; DI int opaque_tid() { int t = threadIdx.x; asm volatile("" : "+v"(t)); return t; }
; DI u16* xres_base(const Params& p) { return (u16*)(p.out + O_Y) + 1024; }
; DI void rowwise_residual(const Params& p, const u16* Y, const float* gpost, int mode, const u16* parts) {
;   const int tid = opaque_tid(), lane = tid & 63, w = tid >> 6;
;   float* y = p.out + O_Y;
;   u16* xr = xres_base(p);
;   float* rs = (float*)(p.ws + W_RS);
;   const int stride = gridDim.x * 4;
;   for (int tb = blockIdx.x * 4 + w; tb < NT; tb += 2 * stride) {
;     float4 yv[2][4], xv[2][4];
;     float ss[2] = {0.f, 0.f};
; #pragma unroll
;     for (int u = 0; u < 2; u++) {
;       const int t = tb + u * stride;
;       if (t < NT) {
; #pragma unroll
;         for (int j = 0; j < 4; j++) {
;           const uint2 yr = ld_nt2u(Y + (long)t * 1024 + j * 256 + lane * 4);
;           yv[u][j] = make_float4(bf2f((u16)(yr.x & 0xffff)), bf2f((u16)(yr.x >> 16)), bf2f((u16)(yr.y & 0xffff)), bf2f((u16)(yr.y >> 16)));
;           if (mode == 0) xv[u][j] = *(const float4*)(xrow(p, t) + j * 256 + lane * 4);
;     ...
;           const float4 g = *(const float4*)(gpost + j * 256 + lane * 4);
.LBB0_1121:
	s_or_b64 exec, exec, s[0:1]
	v_mov_b32_e32 v1, v202
	s_waitcnt lgkmcnt(0)
	s_barrier
	s_movk_i32 s30, 0x4800
	v_ashrrev_i32_e32 v0, 6, v1
	v_add_u32_e32 v0, s65, v0
	v_cmp_gt_i32_e32 vcc, s30, v0
	v_mov_b64_e32 v[2:3], s[48:49]
	s_and_saveexec_b64 s[0:1], vcc
	s_cbranch_execz .LBB0_1136
	v_and_b32_e32 v12, 63, v1
	v_mov_b32_e32 v1, 0
	v_lshlrev_b32_e32 v2, 3, v12
	v_mov_b32_e32 v3, v1
	v_lshl_add_u64 v[8:9], s[48:49], 0, v[2:3]
	s_mov_b64 s[12:13], 0x400000
	v_and_b32_e32 v10, 64, v203
	v_lshl_add_u64 v[4:5], v[8:9], 0, s[12:13]
	s_mov_b64 s[12:13], 0xec00000
	v_add_u32_e32 v10, 64, v10
	v_xor_b32_e32 v11, 32, v203
	v_lshl_add_u64 v[8:9], v[8:9], 0, s[12:13]
	v_cmp_lt_i32_e64 s[12:13], v11, v10
	s_load_dwordx2 s[14:15], s[62:63], 0x58
	s_load_dwordx2 s[16:17], s[62:63], 0xd8
	v_cndmask_b32_e64 v11, v203, v11, s[12:13]
	s_waitcnt vmcnt(8)
	v_lshlrev_b32_e32 v82, 2, v11
	v_xor_b32_e32 v11, 16, v203
	v_cmp_lt_i32_e64 s[12:13], v11, v10
	s_add_u32 s18, s48, 0x10000
	s_addc_u32 s19, s49, 0
	v_cndmask_b32_e64 v11, v203, v11, s[12:13]
	v_lshlrev_b32_e32 v83, 2, v11
	v_xor_b32_e32 v11, 8, v203
	v_cmp_lt_i32_e64 s[12:13], v11, v10
	s_lshl_b32 s20, s50, 3
	v_ashrrev_i32_e32 v17, 31, v0
	v_cndmask_b32_e64 v11, v203, v11, s[12:13]
	v_lshlrev_b32_e32 v84, 2, v11
	v_xor_b32_e32 v11, 4, v203
	v_cmp_lt_i32_e64 s[12:13], v11, v10
	v_mov_b32_e32 v16, v0
	s_mov_b64 s[2:3], 0x10000
	v_cndmask_b32_e64 v11, v203, v11, s[12:13]
	v_lshlrev_b32_e32 v85, 2, v11
	v_xor_b32_e32 v11, 2, v203
	v_cmp_lt_i32_e64 s[12:13], v11, v10
	v_cmp_lt_u32_e32 vcc, 31, v12
	s_ashr_i32 s21, s20, 31
	v_cndmask_b32_e64 v11, v203, v11, s[12:13]
	v_lshlrev_b32_e32 v86, 2, v11
	v_xor_b32_e32 v11, 1, v203
	v_cmp_lt_i32_e64 s[12:13], v11, v10
	v_lshlrev_b64 v[14:15], 12, v[16:17]
	s_waitcnt lgkmcnt(0)
	v_lshl_add_u64 v[6:7], s[16:17], 0, v[2:3]
	v_cndmask_b32_e64 v10, v203, v11, s[12:13]
	v_lshlrev_b32_e32 v87, 2, v10
	v_lshlrev_b32_e32 v10, 4, v12
	v_mov_b32_e32 v11, v1
	v_cmp_eq_u32_e64 s[12:13], 0, v12
	v_lshl_add_u64 v[12:13], v[16:17], 2, s[48:49]
	v_lshlrev_b64 v[16:17], 11, v[16:17]
	v_lshl_add_u64 v[10:11], s[14:15], 0, v[10:11]
	global_load_dwordx4 v[236:239], v[10:11], off
	global_load_dwordx4 v[240:243], v[10:11], off offset:1024
	global_load_dwordx4 v[244:247], v[10:11], off offset:2048
	global_load_dwordx4 v[248:251], v[10:11], off offset:3072
	s_waitcnt vmcnt(0)
	v_lshl_add_u64 v[12:13], v[12:13], 0, s[2:3]
	s_lshl_b64 s[22:23], s[20:21], 2
	v_lshl_add_u64 v[14:15], s[16:17], 0, v[14:15]
	s_lshl_b64 s[24:25], s[20:21], 12
	v_lshl_add_u64 v[16:17], s[48:49], 0, v[16:17]
	s_lshl_b64 s[28:29], s[20:21], 11
	s_mov_b64 s[26:27], 0
	s_mov_b32 s21, 0x400000
	s_movk_i32 s31, 0x7ff
	v_mov_b32_e32 v88, 0x358637bd
	s_mov_b32 s33, 0x800000
	s_movk_i32 s34, 0x47ff
	s_branch .LBB0_1124

; DI unsigned pack2(float a, float b) { f32v2_t v = {a, b}; return __builtin_bit_cast(unsigned, __builtin_convertvector(v, bf16v2_t)); }
; DI void st_nt4(float* q, float4 v) { f32x4n t = {v.x, v.y, v.z, v.w}; __builtin_nontemporal_store(t, (f32x4n*)q); }
; DI void rowwise_residual(const Params& p, const u16* Y, const float* gpost, int mode, const u16* parts) {
;     ...
;     ss[0] = wave_sum(ss[0]); ss[1] = wave_sum(ss[1]);
; #pragma unroll
;     for (int u = 0; u < 2; u++) {
;       const int t = tb + u * stride;
;       if (t < NT) {
;         const float r = rsqrtf(ss[u] * (1.f / 1024.f) + EPS);
;         float s2 = 0.f;
; #pragma unroll
;         for (int j = 0; j < 4; j++) {
;           const float4 g = *(const float4*)(gpost + j * 256 + lane * 4);
;           float4 xn = xv[u][j];
;           xn.x += yv[u][j].x * r * g.x; xn.y += yv[u][j].y * r * g.y; xn.z += yv[u][j].z * r * g.z; xn.w += yv[u][j].w * r * g.w;
;           s2 += xn.x * xn.x + xn.y * xn.y + xn.z * xn.z + xn.w * xn.w;
;           if (mode == 2) st_nt4(y + (long)t * 1024 + j * 256 + lane * 4, xn);
;           else {
;             uint2 o; o.x = pack2(xn.x, xn.y); o.y = pack2(xn.z, xn.w);
;             *(uint2*)(xr + (long)t * XR_LD + j * 256 + lane * 4) = o;
;           }
;         }
;         if (mode != 2) {
;           s2 = wave_sum(s2);
;           if (lane == 0) rs[t] = rsqrtf(s2 * (1.f / 1024.f) + EPS);
;         }
.LBB0_1130:
	s_or_b64 exec, exec, s[2:3]
	s_nop 1
	v_mov_b32_e32 v90, v236
	v_mov_b32_e32 v91, v237
	v_mov_b32_e32 v92, v238
	v_mov_b32_e32 v93, v239
	s_nop 1
	v_add_f32_dpp v235, v78, v78 quad_perm:[1,0,3,2] row_mask:0xf bank_mask:0xf
	s_nop 1
	v_add_f32_dpp v235, v235, v235 quad_perm:[2,3,0,1] row_mask:0xf bank_mask:0xf
	s_nop 1
	v_add_f32_dpp v235, v235, v235 row_half_mirror row_mask:0xf bank_mask:0xf
	s_nop 1
	v_add_f32_dpp v235, v235, v235 row_mirror row_mask:0xf bank_mask:0xf
	s_nop 0
	v_mov_b32_e32 v255, v235
	s_nop 1
	v_permlane16_swap_b32_e32 v235, v255
	s_nop 0
	v_add_f32_e32 v235, v235, v255
	v_mov_b32_e32 v255, v235
	s_nop 1
	v_permlane32_swap_b32_e32 v235, v255
	s_nop 0
	v_add_f32_e32 v235, v235, v255
	v_mov_b32_e32 v94, v72
	v_mov_b32_e32 v95, v70
	v_mov_b32_e32 v96, v74
	v_mov_b32_e32 v97, v76
	s_waitcnt lgkmcnt(0)
	v_mov_b32_e32 v76, v75
	s_waitcnt lgkmcnt(0)
	s_waitcnt lgkmcnt(0)
	s_waitcnt lgkmcnt(0)
	s_waitcnt vmcnt(0)
	v_lshlrev_b32_e32 v78, 16, v64
	s_waitcnt lgkmcnt(0)
	v_and_b32_e32 v79, 0xffff0000, v64
	v_lshlrev_b32_e32 v64, 16, v65
	v_and_b32_e32 v65, 0xffff0000, v65
	s_waitcnt lgkmcnt(0)
	v_mov_b32_e32 v72, v235
	v_fmamk_f32 v72, v72, 0x3a800000, v88
	v_mul_f32_e32 v80, 0x4b800000, v72
	v_cmp_gt_f32_e64 s[16:17], s33, v72
	s_nop 1
	v_cndmask_b32_e64 v72, v72, v80, s[16:17]
	v_rsq_f32_e32 v72, v72
	s_nop 1
	v_add_f32_dpp v229, v81, v81 quad_perm:[1,0,3,2] row_mask:0xf bank_mask:0xf
	s_nop 1
	v_add_f32_dpp v229, v229, v229 quad_perm:[2,3,0,1] row_mask:0xf bank_mask:0xf
	s_nop 1
	v_add_f32_dpp v229, v229, v229 row_half_mirror row_mask:0xf bank_mask:0xf
	s_nop 1
	v_add_f32_dpp v229, v229, v229 row_mirror row_mask:0xf bank_mask:0xf
	s_nop 0
	v_mov_b32_e32 v255, v229
	s_nop 1
	v_permlane16_swap_b32_e32 v229, v255
	s_nop 0
	v_add_f32_e32 v229, v229, v255
	v_mov_b32_e32 v255, v229
	s_nop 1
	v_permlane32_swap_b32_e32 v229, v255
	s_nop 0
	v_add_f32_e32 v229, v229, v255
	v_mul_f32_e32 v70, 0x45800000, v72
	v_cndmask_b32_e64 v72, v72, v70, s[16:17]
	v_pk_mul_f32 v[94:95], v[72:73], v[94:95] op_sel_hi:[0,1]
	v_pk_mul_f32 v[96:97], v[72:73], v[96:97] op_sel_hi:[0,1]
	v_mov_b32_e32 v70, v73
	v_pk_mul_f32 v[70:71], v[72:73], v[70:71] op_sel_hi:[0,1]
	v_pk_mul_f32 v[74:75], v[72:73], v[76:77] op_sel_hi:[0,1]
	v_lshlrev_b32_e32 v76, 16, v56
	v_and_b32_e32 v77, 0xffff0000, v56
	v_lshlrev_b32_e32 v56, 16, v57
	v_and_b32_e32 v57, 0xffff0000, v57
	v_pk_mul_f32 v[68:69], v[72:73], v[68:69] op_sel_hi:[0,1]
	v_pk_mul_f32 v[66:67], v[72:73], v[66:67] op_sel_hi:[0,1]
	v_pk_mul_f32 v[60:61], v[60:61], v[72:73] op_sel_hi:[1,0]
	v_pk_mul_f32 v[58:59], v[58:59], v[72:73] op_sel_hi:[1,0]
	v_pk_fma_f32 v[78:79], v[90:91], v[94:95], v[78:79]
	v_pk_fma_f32 v[94:95], v[92:93], v[96:97], v[64:65]
	v_cvt_pk_bf16_f32 v64, v78, v79
	v_cvt_pk_bf16_f32 v65, v94, v95
	global_store_dwordx2 v[52:53], v[64:65], off offset:2048
	s_nop 1
	v_mov_b32_e32 v90, v240
	v_mov_b32_e32 v91, v241
	v_mov_b32_e32 v92, v242
	v_mov_b32_e32 v93, v243
	v_lshlrev_b32_e32 v64, 16, v62
	v_and_b32_e32 v65, 0xffff0000, v62
	v_lshlrev_b32_e32 v62, 16, v63
	v_and_b32_e32 v63, 0xffff0000, v63
	v_pk_mul_f32 v[72:73], v[78:79], v[78:79]
	v_pk_fma_f32 v[70:71], v[70:71], v[90:91], v[64:65]
	v_pk_fma_f32 v[74:75], v[74:75], v[92:93], v[62:63]
	v_cvt_pk_bf16_f32 v62, v70, v71
	v_cvt_pk_bf16_f32 v63, v74, v75
	global_store_dwordx2 v[52:53], v[62:63], off offset:2560
	s_nop 1
	v_mov_b32_e32 v62, v244
	v_mov_b32_e32 v63, v245
	v_mov_b32_e32 v64, v246
	v_mov_b32_e32 v65, v247
	v_add_f32_e32 v72, v72, v73
	v_pk_mul_f32 v[70:71], v[70:71], v[70:71]
	v_pk_fma_f32 v[68:69], v[68:69], v[62:63], v[76:77]
	v_pk_fma_f32 v[56:57], v[66:67], v[64:65], v[56:57]
	v_cvt_pk_bf16_f32 v62, v68, v69
	v_cvt_pk_bf16_f32 v63, v56, v57
	global_store_dwordx2 v[52:53], v[62:63], off offset:3072
	s_nop 1
	v_mov_b32_e32 v62, v248
	v_mov_b32_e32 v63, v249
	v_mov_b32_e32 v64, v250
	v_mov_b32_e32 v65, v251
	v_pk_mul_f32 v[76:77], v[94:95], v[94:95]
	v_lshlrev_b32_e32 v66, 16, v54
	v_and_b32_e32 v67, 0xffff0000, v54
	v_add_f32_e32 v72, v76, v72
	v_pk_mul_f32 v[68:69], v[68:69], v[68:69]
	v_lshlrev_b32_e32 v54, 16, v55
	v_and_b32_e32 v55, 0xffff0000, v55
	v_add_f32_e32 v76, v77, v72
	v_pk_mul_f32 v[72:73], v[74:75], v[74:75]
	v_add_f32_e32 v70, v70, v71
	v_pk_mul_f32 v[56:57], v[56:57], v[56:57]
	v_add_f32_e32 v68, v68, v69
	v_add_f32_e32 v70, v70, v72
	v_add_f32_e32 v56, v68, v56
	v_add_f32_e32 v70, v70, v73
	v_add_f32_e32 v68, v56, v57
	v_add_f32_e32 v70, v76, v70
	v_pk_fma_f32 v[60:61], v[60:61], v[62:63], v[66:67]
	v_pk_fma_f32 v[58:59], v[58:59], v[64:65], v[54:55]
	v_pk_mul_f32 v[54:55], v[60:61], v[60:61]
	v_pk_mul_f32 v[56:57], v[58:59], v[58:59]
	v_add_f32_e32 v54, v54, v55
	v_add_f32_e32 v54, v54, v56
	v_add_f32_e32 v62, v70, v68
	v_add_f32_e32 v54, v54, v57
	v_add_f32_e32 v54, v62, v54
	s_nop 1
	v_add_f32_dpp v228, v54, v54 quad_perm:[1,0,3,2] row_mask:0xf bank_mask:0xf
	s_nop 1
	v_add_f32_dpp v228, v228, v228 quad_perm:[2,3,0,1] row_mask:0xf bank_mask:0xf
	s_nop 1
	v_add_f32_dpp v228, v228, v228 row_half_mirror row_mask:0xf bank_mask:0xf
	s_nop 1
	v_add_f32_dpp v228, v228, v228 row_mirror row_mask:0xf bank_mask:0xf
	s_nop 0
	v_mov_b32_e32 v255, v228
	s_nop 1
	v_permlane16_swap_b32_e32 v228, v255
	s_nop 0
	v_add_f32_e32 v228, v228, v255
	v_mov_b32_e32 v255, v228
	s_nop 1
	v_permlane32_swap_b32_e32 v228, v255
	s_nop 0
	v_add_f32_e32 v228, v228, v255
	s_waitcnt lgkmcnt(1)
	v_cvt_pk_bf16_f32 v60, v60, v61
	v_cvt_pk_bf16_f32 v61, v58, v59
	s_waitcnt lgkmcnt(1)
	s_waitcnt lgkmcnt(1)
	global_store_dwordx2 v[52:53], v[60:61], off offset:3584
	s_waitcnt lgkmcnt(1)
	s_waitcnt lgkmcnt(1)
	s_waitcnt lgkmcnt(1)
	s_waitcnt lgkmcnt(1)
	s_waitcnt lgkmcnt(1)
	s_waitcnt lgkmcnt(1)
	s_waitcnt lgkmcnt(1)
	s_and_saveexec_b64 s[2:3], s[12:13]
	s_cbranch_execz .LBB0_1132
	s_waitcnt lgkmcnt(0)
	v_mov_b32_e32 v52, v228
	v_fmamk_f32 v52, v52, 0x3a800000, v88
	v_mul_f32_e32 v53, 0x4b800000, v52
	v_cmp_gt_f32_e64 s[16:17], s33, v52
	s_nop 1
	v_cndmask_b32_e64 v52, v52, v53, s[16:17]
	v_rsq_f32_e32 v52, v52
	s_nop 0
	v_mul_f32_e32 v53, 0x45800000, v52
	v_cndmask_b32_e64 v52, v52, v53, s[16:17]
	global_store_dword v[12:13], v52, off
; DI unsigned pack2(float a, float b) { f32v2_t v = {a, b}; return __builtin_bit_cast(unsigned, __builtin_convertvector(v, bf16v2_t)); }
; DI void st_nt4(float* q, float4 v) { f32x4n t = {v.x, v.y, v.z, v.w}; __builtin_nontemporal_store(t, (f32x4n*)q); }
; DI void rowwise_residual(const Params& p, const u16* Y, const float* gpost, int mode, const u16* parts) {
;     ...
;     for (int u = 0; u < 2; u++) {
;       const int t = tb + u * stride;
;       if (t < NT) {
;         const float r = rsqrtf(ss[u] * (1.f / 1024.f) + EPS);
;         float s2 = 0.f;
; #pragma unroll
;         for (int j = 0; j < 4; j++) {
;           const float4 g = *(const float4*)(gpost + j * 256 + lane * 4);
;           float4 xn = xv[u][j];
;           xn.x += yv[u][j].x * r * g.x; xn.y += yv[u][j].y * r * g.y; xn.z += yv[u][j].z * r * g.z; xn.w += yv[u][j].w * r * g.w;
;           s2 += xn.x * xn.x + xn.y * xn.y + xn.z * xn.z + xn.w * xn.w;
;           if (mode == 2) st_nt4(y + (long)t * 1024 + j * 256 + lane * 4, xn);
;           else {
;             uint2 o; o.x = pack2(xn.x, xn.y); o.y = pack2(xn.z, xn.w);
;             *(uint2*)(xr + (long)t * XR_LD + j * 256 + lane * 4) = o;
;           }
;         }
;         if (mode != 2) {
;           s2 = wave_sum(s2);
;           if (lane == 0) rs[t] = rsqrtf(s2 * (1.f / 1024.f) + EPS);
;         }
.LBB0_1132:
	s_or_b64 exec, exec, s[2:3]
	s_and_saveexec_b64 s[2:3], s[14:15]
	s_cbranch_execz .LBB0_1123
	s_waitcnt lgkmcnt(0)
	s_nop 1
	v_mov_b32_e32 v56, v236
	v_mov_b32_e32 v57, v237
	v_mov_b32_e32 v58, v238
	v_mov_b32_e32 v59, v239
	v_mov_b32_e32 v52, v229
	v_fmamk_f32 v52, v52, 0x3a800000, v88
	v_mul_f32_e32 v53, 0x4b800000, v52
	v_cmp_gt_f32_e64 s[14:15], s33, v52
	s_nop 1
	v_cndmask_b32_e64 v52, v52, v53, s[14:15]
	v_rsq_f32_e32 v54, v52
	v_lshlrev_b64 v[52:53], 12, v[50:51]
	v_lshl_add_u64 v[60:61], v[6:7], 0, v[52:53]
	v_mul_f32_e32 v52, 0x45800000, v54
	v_cndmask_b32_e64 v62, v54, v52, s[14:15]
	v_pk_mul_f32 v[52:53], v[22:23], v[62:63] op_sel_hi:[1,0]
	v_pk_mul_f32 v[54:55], v[24:25], v[62:63] op_sel_hi:[1,0]
	v_pk_mul_f32 v[64:65], v[30:31], v[62:63] op_sel_hi:[1,0]
	v_pk_mul_f32 v[66:67], v[32:33], v[62:63] op_sel_hi:[1,0]
	v_pk_mul_f32 v[68:69], v[40:41], v[62:63] op_sel_hi:[1,0]
	v_pk_mul_f32 v[70:71], v[38:39], v[62:63] op_sel_hi:[1,0]
	v_pk_mul_f32 v[72:73], v[18:19], v[62:63] op_sel_hi:[1,0]
	v_pk_mul_f32 v[62:63], v[20:21], v[62:63] op_sel_hi:[1,0]
	v_pk_fma_f32 v[56:57], v[52:53], v[56:57], v[28:29]
	v_pk_fma_f32 v[58:59], v[54:55], v[58:59], v[26:27]
	v_cvt_pk_bf16_f32 v52, v56, v57
	v_cvt_pk_bf16_f32 v53, v58, v59
	global_store_dwordx2 v[60:61], v[52:53], off offset:2048
	s_nop 1
	v_mov_b32_e32 v52, v240
	v_mov_b32_e32 v53, v241
	v_mov_b32_e32 v54, v242
	v_mov_b32_e32 v55, v243
	v_pk_mul_f32 v[56:57], v[56:57], v[56:57]
	v_pk_mul_f32 v[58:59], v[58:59], v[58:59]
	v_add_f32_e32 v56, v56, v57
	v_add_f32_e32 v56, v56, v58
	v_add_f32_e32 v74, v56, v59
	v_pk_fma_f32 v[64:65], v[64:65], v[52:53], v[36:37]
	v_pk_fma_f32 v[66:67], v[66:67], v[54:55], v[34:35]
	v_cvt_pk_bf16_f32 v52, v64, v65
	v_cvt_pk_bf16_f32 v53, v66, v67
	global_store_dwordx2 v[60:61], v[52:53], off offset:2560
	s_nop 1
	v_mov_b32_e32 v52, v244
	v_mov_b32_e32 v53, v245
	v_mov_b32_e32 v54, v246
	v_mov_b32_e32 v55, v247
	v_pk_mul_f32 v[56:57], v[64:65], v[64:65]
	v_pk_mul_f32 v[58:59], v[66:67], v[66:67]
	v_add_f32_e32 v56, v56, v57
	v_add_f32_e32 v56, v56, v58
	v_add_f32_e32 v56, v56, v59
	v_add_f32_e32 v64, v74, v56
	v_pk_fma_f32 v[68:69], v[68:69], v[52:53], v[44:45]
	v_pk_fma_f32 v[70:71], v[70:71], v[54:55], v[42:43]
	v_cvt_pk_bf16_f32 v52, v68, v69
	v_cvt_pk_bf16_f32 v53, v70, v71
	global_store_dwordx2 v[60:61], v[52:53], off offset:3072
	s_nop 1
	v_mov_b32_e32 v52, v248
	v_mov_b32_e32 v53, v249
	v_mov_b32_e32 v54, v250
	v_mov_b32_e32 v55, v251
	v_pk_mul_f32 v[56:57], v[68:69], v[68:69]
	v_pk_mul_f32 v[58:59], v[70:71], v[70:71]
	v_add_f32_e32 v56, v56, v57
	v_add_f32_e32 v56, v56, v58
	v_add_f32_e32 v65, v56, v59
	v_pk_fma_f32 v[56:57], v[72:73], v[52:53], v[48:49]
	v_pk_fma_f32 v[54:55], v[62:63], v[54:55], v[46:47]
	v_pk_mul_f32 v[52:53], v[56:57], v[56:57]
	v_pk_mul_f32 v[58:59], v[54:55], v[54:55]
	v_add_f32_e32 v52, v52, v53
	v_add_f32_e32 v52, v52, v58
	v_add_f32_e32 v62, v64, v65
	v_add_f32_e32 v52, v52, v59
	v_add_f32_e32 v52, v62, v52
	s_nop 1
	v_add_f32_dpp v230, v52, v52 quad_perm:[1,0,3,2] row_mask:0xf bank_mask:0xf
	s_nop 1
	v_add_f32_dpp v230, v230, v230 quad_perm:[2,3,0,1] row_mask:0xf bank_mask:0xf
	s_nop 1
	v_add_f32_dpp v230, v230, v230 row_half_mirror row_mask:0xf bank_mask:0xf
	s_nop 1
	v_add_f32_dpp v230, v230, v230 row_mirror row_mask:0xf bank_mask:0xf
	s_nop 0
	v_mov_b32_e32 v255, v230
	s_nop 1
	v_permlane16_swap_b32_e32 v230, v255
	s_nop 0
	v_add_f32_e32 v230, v230, v255
	v_mov_b32_e32 v255, v230
	s_nop 1
	v_permlane32_swap_b32_e32 v230, v255
	s_nop 0
	v_add_f32_e32 v230, v230, v255
	v_cvt_pk_bf16_f32 v56, v56, v57
	v_cvt_pk_bf16_f32 v57, v54, v55
	global_store_dwordx2 v[60:61], v[56:57], off offset:3584
	s_waitcnt lgkmcnt(0)
	s_waitcnt lgkmcnt(0)
	s_waitcnt lgkmcnt(0)
	s_waitcnt lgkmcnt(0)
	s_waitcnt lgkmcnt(0)
	s_and_b64 exec, exec, s[12:13]
	s_cbranch_execz .LBB0_1123
	s_waitcnt lgkmcnt(0)
	v_mov_b32_e32 v52, v230
	v_fmamk_f32 v52, v52, 0x3a800000, v88
	v_mul_f32_e32 v53, 0x4b800000, v52
	v_cmp_gt_f32_e64 s[14:15], s33, v52
	v_lshl_add_u64 v[50:51], v[50:51], 2, s[18:19]
	s_nop 0
	v_cndmask_b32_e64 v52, v52, v53, s[14:15]
	v_rsq_f32_e32 v52, v52
	s_nop 0
	v_mul_f32_e32 v53, 0x45800000, v52
	v_cndmask_b32_e64 v52, v52, v53, s[14:15]
	global_store_dword v[50:51], v52, off
	s_branch .LBB0_1123

; DI float bf2f(u16 h) { return __uint_as_float(((unsigned)h) << 16); }
; DI uint2 ld_nt2u(const void* q) { const u32x2n v = __builtin_nontemporal_load((const u32x2n*)q); return make_uint2(v.x, v.y); }
; DI int opaque_tid() { int t = threadIdx.x; asm volatile("" : "+v"(t)); return t; }
; DI u16* xres_base(const Params& p) { return (u16*)(p.out + O_Y) + 1024; }
; DI void rowwise_residual(const Params& p, const u16* Y, const float* gpost, int mode, const u16* parts) {
;   const int tid = opaque_tid(), lane = tid & 63, w = tid >> 6;
;   float* y = p.out + O_Y;
;   u16* xr = xres_base(p);
;   float* rs = (float*)(p.ws + W_RS);
;   const int stride = gridDim.x * 4;
;   for (int tb = blockIdx.x * 4 + w; tb < NT; tb += 2 * stride) {
;     float4 yv[2][4], xv[2][4];
;     float ss[2] = {0.f, 0.f};
; #pragma unroll
;     for (int u = 0; u < 2; u++) {
;       const int t = tb + u * stride;
;       if (t < NT) {
; #pragma unroll
;         for (int j = 0; j < 4; j++) {
;           const uint2 yr = ld_nt2u(Y + (long)t * 1024 + j * 256 + lane * 4);
;           yv[u][j] = make_float4(bf2f((u16)(yr.x & 0xffff)), bf2f((u16)(yr.x >> 16)), bf2f((u16)(yr.y & 0xffff)), bf2f((u16)(yr.y >> 16)));
;           if (mode == 0) xv[u][j] = *(const float4*)(xrow(p, t) + j * 256 + lane * 4);
;     ...
;           const float4 g = *(const float4*)(gpost + j * 256 + lane * 4);
.LBB0_1607:
	s_or_b64 exec, exec, s[0:1]
	v_mov_b32_e32 v1, v202
	s_waitcnt lgkmcnt(0)
	s_barrier
	s_movk_i32 s28, 0x4800
	v_ashrrev_i32_e32 v0, 6, v1
	v_add_u32_e32 v0, s65, v0
	v_cmp_gt_i32_e32 vcc, s28, v0
	v_mov_b64_e32 v[2:3], s[48:49]
	s_and_saveexec_b64 s[0:1], vcc
	s_cbranch_execz .LBB0_1622
	v_and_b32_e32 v12, 63, v1
	v_mov_b32_e32 v1, 0
	v_lshlrev_b32_e32 v2, 3, v12
	v_mov_b32_e32 v3, v1
	v_lshl_add_u64 v[8:9], s[48:49], 0, v[2:3]
	s_mov_b64 s[6:7], 0x2800000
	v_and_b32_e32 v10, 64, v203
	v_lshl_add_u64 v[4:5], v[8:9], 0, s[6:7]
	s_mov_b64 s[6:7], 0x9400000
	v_add_u32_e32 v10, 64, v10
	v_xor_b32_e32 v11, 32, v203
	v_lshl_add_u64 v[8:9], v[8:9], 0, s[6:7]
	v_cmp_lt_i32_e64 s[6:7], v11, v10
	s_load_dwordx2 s[12:13], s[62:63], 0x48
	s_load_dwordx2 s[14:15], s[62:63], 0xd8
	v_cndmask_b32_e64 v11, v203, v11, s[6:7]
	v_lshlrev_b32_e32 v82, 2, v11
	v_xor_b32_e32 v11, 16, v203
	v_cmp_lt_i32_e64 s[6:7], v11, v10
	s_add_u32 s16, s48, 0x10000
	s_addc_u32 s17, s49, 0
	v_cndmask_b32_e64 v11, v203, v11, s[6:7]
	v_lshlrev_b32_e32 v83, 2, v11
	v_xor_b32_e32 v11, 8, v203
	v_cmp_lt_i32_e64 s[6:7], v11, v10
	s_lshl_b32 s18, s50, 3
	v_ashrrev_i32_e32 v17, 31, v0
	v_cndmask_b32_e64 v11, v203, v11, s[6:7]
	v_lshlrev_b32_e32 v84, 2, v11
	v_xor_b32_e32 v11, 4, v203
	v_cmp_lt_i32_e64 s[6:7], v11, v10
	v_mov_b32_e32 v16, v0
	s_mov_b64 s[2:3], 0x10000
	v_cndmask_b32_e64 v11, v203, v11, s[6:7]
	v_lshlrev_b32_e32 v85, 2, v11
	v_xor_b32_e32 v11, 2, v203
	v_cmp_lt_i32_e64 s[6:7], v11, v10
	v_cmp_lt_u32_e32 vcc, 31, v12
	s_ashr_i32 s19, s18, 31
	v_cndmask_b32_e64 v11, v203, v11, s[6:7]
	v_lshlrev_b32_e32 v86, 2, v11
	v_xor_b32_e32 v11, 1, v203
	v_cmp_lt_i32_e64 s[6:7], v11, v10
	v_lshlrev_b64 v[14:15], 12, v[16:17]
	s_waitcnt lgkmcnt(0)
	v_lshl_add_u64 v[6:7], s[14:15], 0, v[2:3]
	v_cndmask_b32_e64 v10, v203, v11, s[6:7]
	v_lshlrev_b32_e32 v87, 2, v10
	v_lshlrev_b32_e32 v10, 4, v12
	v_mov_b32_e32 v11, v1
	v_lshl_add_u64 v[10:11], s[12:13], 0, v[10:11]
	s_mov_b64 s[6:7], 0x1000
	v_lshl_add_u64 v[10:11], v[10:11], 0, s[6:7]
	global_load_dwordx4 v[236:239], v[10:11], off
	global_load_dwordx4 v[240:243], v[10:11], off offset:1024
	global_load_dwordx4 v[244:247], v[10:11], off offset:2048
	global_load_dwordx4 v[248:251], v[10:11], off offset:3072
	s_waitcnt vmcnt(0)
	v_cmp_eq_u32_e64 s[6:7], 0, v12
	v_lshl_add_u64 v[12:13], v[16:17], 2, s[48:49]
	v_lshlrev_b64 v[16:17], 11, v[16:17]
	v_lshl_add_u64 v[12:13], v[12:13], 0, s[2:3]
	s_lshl_b64 s[20:21], s[18:19], 2
	v_lshl_add_u64 v[14:15], s[14:15], 0, v[14:15]
	s_lshl_b64 s[22:23], s[18:19], 12
	v_lshl_add_u64 v[16:17], s[48:49], 0, v[16:17]
	s_lshl_b64 s[26:27], s[18:19], 11
	s_mov_b64 s[24:25], 0
	s_mov_b32 s19, 0x2800000
	s_movk_i32 s29, 0x7ff
	v_mov_b32_e32 v88, 0x358637bd
	s_mov_b32 s30, 0x800000
	s_movk_i32 s31, 0x47ff
	s_branch .LBB0_1610

; DI unsigned pack2(float a, float b) { f32v2_t v = {a, b}; return __builtin_bit_cast(unsigned, __builtin_convertvector(v, bf16v2_t)); }
; DI void st_nt4(float* q, float4 v) { f32x4n t = {v.x, v.y, v.z, v.w}; __builtin_nontemporal_store(t, (f32x4n*)q); }
; DI void rowwise_residual(const Params& p, const u16* Y, const float* gpost, int mode, const u16* parts) {
;     ...
;     ss[0] = wave_sum(ss[0]); ss[1] = wave_sum(ss[1]);
; #pragma unroll
;     for (int u = 0; u < 2; u++) {
;       const int t = tb + u * stride;
;       if (t < NT) {
;         const float r = rsqrtf(ss[u] * (1.f / 1024.f) + EPS);
;         float s2 = 0.f;
; #pragma unroll
;         for (int j = 0; j < 4; j++) {
;           const float4 g = *(const float4*)(gpost + j * 256 + lane * 4);
;           float4 xn = xv[u][j];
;           xn.x += yv[u][j].x * r * g.x; xn.y += yv[u][j].y * r * g.y; xn.z += yv[u][j].z * r * g.z; xn.w += yv[u][j].w * r * g.w;
;           s2 += xn.x * xn.x + xn.y * xn.y + xn.z * xn.z + xn.w * xn.w;
;           if (mode == 2) st_nt4(y + (long)t * 1024 + j * 256 + lane * 4, xn);
;           else {
;             uint2 o; o.x = pack2(xn.x, xn.y); o.y = pack2(xn.z, xn.w);
;             *(uint2*)(xr + (long)t * XR_LD + j * 256 + lane * 4) = o;
;           }
;         }
;         if (mode != 2) {
;           s2 = wave_sum(s2);
;           if (lane == 0) rs[t] = rsqrtf(s2 * (1.f / 1024.f) + EPS);
;         }
.LBB0_1616:
	s_or_b64 exec, exec, s[2:3]
	s_nop 1
	v_mov_b32_e32 v90, v236
	v_mov_b32_e32 v91, v237
	v_mov_b32_e32 v92, v238
	v_mov_b32_e32 v93, v239
	s_nop 1
	v_add_f32_dpp v231, v78, v78 quad_perm:[1,0,3,2] row_mask:0xf bank_mask:0xf
	s_nop 1
	v_add_f32_dpp v231, v231, v231 quad_perm:[2,3,0,1] row_mask:0xf bank_mask:0xf
	s_nop 1
	v_add_f32_dpp v231, v231, v231 row_half_mirror row_mask:0xf bank_mask:0xf
	s_nop 1
	v_add_f32_dpp v231, v231, v231 row_mirror row_mask:0xf bank_mask:0xf
	s_nop 0
	v_mov_b32_e32 v255, v231
	s_nop 1
	v_permlane16_swap_b32_e32 v231, v255
	s_nop 0
	v_add_f32_e32 v231, v231, v255
	v_mov_b32_e32 v255, v231
	s_nop 1
	v_permlane32_swap_b32_e32 v231, v255
	s_nop 0
	v_add_f32_e32 v231, v231, v255
	v_mov_b32_e32 v94, v72
	v_mov_b32_e32 v95, v70
	v_mov_b32_e32 v96, v74
	v_mov_b32_e32 v97, v76
	s_waitcnt lgkmcnt(0)
	v_mov_b32_e32 v76, v75
	s_waitcnt lgkmcnt(0)
	s_waitcnt lgkmcnt(0)
	s_waitcnt lgkmcnt(0)
	s_waitcnt vmcnt(0)
	v_lshlrev_b32_e32 v78, 16, v64
	s_waitcnt lgkmcnt(0)
	v_and_b32_e32 v79, 0xffff0000, v64
	v_lshlrev_b32_e32 v64, 16, v65
	v_and_b32_e32 v65, 0xffff0000, v65
	s_waitcnt lgkmcnt(0)
	v_mov_b32_e32 v72, v231
	v_fmamk_f32 v72, v72, 0x3a800000, v88
	v_mul_f32_e32 v80, 0x4b800000, v72
	v_cmp_gt_f32_e64 s[14:15], s30, v72
	s_nop 1
	v_cndmask_b32_e64 v72, v72, v80, s[14:15]
	v_rsq_f32_e32 v72, v72
	s_nop 1
	v_add_f32_dpp v233, v81, v81 quad_perm:[1,0,3,2] row_mask:0xf bank_mask:0xf
	s_nop 1
	v_add_f32_dpp v233, v233, v233 quad_perm:[2,3,0,1] row_mask:0xf bank_mask:0xf
	s_nop 1
	v_add_f32_dpp v233, v233, v233 row_half_mirror row_mask:0xf bank_mask:0xf
	s_nop 1
	v_add_f32_dpp v233, v233, v233 row_mirror row_mask:0xf bank_mask:0xf
	s_nop 0
	v_mov_b32_e32 v255, v233
	s_nop 1
	v_permlane16_swap_b32_e32 v233, v255
	s_nop 0
	v_add_f32_e32 v233, v233, v255
	v_mov_b32_e32 v255, v233
	s_nop 1
	v_permlane32_swap_b32_e32 v233, v255
	s_nop 0
	v_add_f32_e32 v233, v233, v255
	v_mul_f32_e32 v70, 0x45800000, v72
	v_cndmask_b32_e64 v72, v72, v70, s[14:15]
	v_pk_mul_f32 v[94:95], v[72:73], v[94:95] op_sel_hi:[0,1]
	v_pk_mul_f32 v[96:97], v[72:73], v[96:97] op_sel_hi:[0,1]
	v_mov_b32_e32 v70, v73
	v_pk_mul_f32 v[70:71], v[72:73], v[70:71] op_sel_hi:[0,1]
	v_pk_mul_f32 v[74:75], v[72:73], v[76:77] op_sel_hi:[0,1]
	v_lshlrev_b32_e32 v76, 16, v56
	v_and_b32_e32 v77, 0xffff0000, v56
	v_lshlrev_b32_e32 v56, 16, v57
	v_and_b32_e32 v57, 0xffff0000, v57
	v_pk_mul_f32 v[68:69], v[72:73], v[68:69] op_sel_hi:[0,1]
	v_pk_mul_f32 v[66:67], v[72:73], v[66:67] op_sel_hi:[0,1]
	v_pk_mul_f32 v[60:61], v[60:61], v[72:73] op_sel_hi:[1,0]
	v_pk_mul_f32 v[58:59], v[58:59], v[72:73] op_sel_hi:[1,0]
	v_pk_fma_f32 v[78:79], v[90:91], v[94:95], v[78:79]
	v_pk_fma_f32 v[94:95], v[92:93], v[96:97], v[64:65]
	v_cvt_pk_bf16_f32 v64, v78, v79
	v_cvt_pk_bf16_f32 v65, v94, v95
	global_store_dwordx2 v[52:53], v[64:65], off offset:2048
	s_nop 1
	v_mov_b32_e32 v90, v240
	v_mov_b32_e32 v91, v241
	v_mov_b32_e32 v92, v242
	v_mov_b32_e32 v93, v243
	v_lshlrev_b32_e32 v64, 16, v62
	v_and_b32_e32 v65, 0xffff0000, v62
	v_lshlrev_b32_e32 v62, 16, v63
	v_and_b32_e32 v63, 0xffff0000, v63
	v_pk_mul_f32 v[72:73], v[78:79], v[78:79]
	v_pk_fma_f32 v[70:71], v[70:71], v[90:91], v[64:65]
	v_pk_fma_f32 v[74:75], v[74:75], v[92:93], v[62:63]
	v_cvt_pk_bf16_f32 v62, v70, v71
	v_cvt_pk_bf16_f32 v63, v74, v75
	global_store_dwordx2 v[52:53], v[62:63], off offset:2560
	s_nop 1
	v_mov_b32_e32 v62, v244
	v_mov_b32_e32 v63, v245
	v_mov_b32_e32 v64, v246
	v_mov_b32_e32 v65, v247
	v_add_f32_e32 v72, v72, v73
	v_pk_mul_f32 v[70:71], v[70:71], v[70:71]
	v_pk_fma_f32 v[68:69], v[68:69], v[62:63], v[76:77]
	v_pk_fma_f32 v[56:57], v[66:67], v[64:65], v[56:57]
	v_cvt_pk_bf16_f32 v62, v68, v69
	v_cvt_pk_bf16_f32 v63, v56, v57
	global_store_dwordx2 v[52:53], v[62:63], off offset:3072
	s_nop 1
	v_mov_b32_e32 v62, v248
	v_mov_b32_e32 v63, v249
	v_mov_b32_e32 v64, v250
	v_mov_b32_e32 v65, v251
	v_pk_mul_f32 v[76:77], v[94:95], v[94:95]
	v_lshlrev_b32_e32 v66, 16, v54
	v_and_b32_e32 v67, 0xffff0000, v54
	v_add_f32_e32 v72, v76, v72
	v_pk_mul_f32 v[68:69], v[68:69], v[68:69]
	v_lshlrev_b32_e32 v54, 16, v55
	v_and_b32_e32 v55, 0xffff0000, v55
	v_add_f32_e32 v76, v77, v72
	v_pk_mul_f32 v[72:73], v[74:75], v[74:75]
	v_add_f32_e32 v70, v70, v71
	v_pk_mul_f32 v[56:57], v[56:57], v[56:57]
	v_add_f32_e32 v68, v68, v69
	v_add_f32_e32 v70, v70, v72
	v_add_f32_e32 v56, v68, v56
	v_add_f32_e32 v70, v70, v73
	v_add_f32_e32 v68, v56, v57
	v_add_f32_e32 v70, v76, v70
	v_pk_fma_f32 v[60:61], v[60:61], v[62:63], v[66:67]
	v_pk_fma_f32 v[58:59], v[58:59], v[64:65], v[54:55]
	v_pk_mul_f32 v[54:55], v[60:61], v[60:61]
	v_pk_mul_f32 v[56:57], v[58:59], v[58:59]
	v_add_f32_e32 v54, v54, v55
	v_add_f32_e32 v54, v54, v56
	v_add_f32_e32 v62, v70, v68
	v_add_f32_e32 v54, v54, v57
	v_add_f32_e32 v54, v62, v54
	s_nop 1
	v_add_f32_dpp v232, v54, v54 quad_perm:[1,0,3,2] row_mask:0xf bank_mask:0xf
	s_nop 1
	v_add_f32_dpp v232, v232, v232 quad_perm:[2,3,0,1] row_mask:0xf bank_mask:0xf
	s_nop 1
	v_add_f32_dpp v232, v232, v232 row_half_mirror row_mask:0xf bank_mask:0xf
	s_nop 1
	v_add_f32_dpp v232, v232, v232 row_mirror row_mask:0xf bank_mask:0xf
	s_nop 0
	v_mov_b32_e32 v255, v232
	s_nop 1
	v_permlane16_swap_b32_e32 v232, v255
	s_nop 0
	v_add_f32_e32 v232, v232, v255
	v_mov_b32_e32 v255, v232
	s_nop 1
	v_permlane32_swap_b32_e32 v232, v255
	s_nop 0
	v_add_f32_e32 v232, v232, v255
	s_waitcnt lgkmcnt(1)
	v_cvt_pk_bf16_f32 v60, v60, v61
	v_cvt_pk_bf16_f32 v61, v58, v59
	s_waitcnt lgkmcnt(1)
	s_waitcnt lgkmcnt(1)
	global_store_dwordx2 v[52:53], v[60:61], off offset:3584
	s_waitcnt lgkmcnt(1)
	s_waitcnt lgkmcnt(1)
	s_waitcnt lgkmcnt(1)
	s_waitcnt lgkmcnt(1)
	s_waitcnt lgkmcnt(1)
	s_waitcnt lgkmcnt(1)
	s_waitcnt lgkmcnt(1)
	s_and_saveexec_b64 s[2:3], s[6:7]
	s_cbranch_execz .LBB0_1618
	s_waitcnt lgkmcnt(0)
	v_mov_b32_e32 v52, v232
	v_fmamk_f32 v52, v52, 0x3a800000, v88
	v_mul_f32_e32 v53, 0x4b800000, v52
	v_cmp_gt_f32_e64 s[14:15], s30, v52
	s_nop 1
	v_cndmask_b32_e64 v52, v52, v53, s[14:15]
	v_rsq_f32_e32 v52, v52
	s_nop 0
	v_mul_f32_e32 v53, 0x45800000, v52
	v_cndmask_b32_e64 v52, v52, v53, s[14:15]
	global_store_dword v[12:13], v52, off
; DI unsigned pack2(float a, float b) { f32v2_t v = {a, b}; return __builtin_bit_cast(unsigned, __builtin_convertvector(v, bf16v2_t)); }
; DI void st_nt4(float* q, float4 v) { f32x4n t = {v.x, v.y, v.z, v.w}; __builtin_nontemporal_store(t, (f32x4n*)q); }
; DI void rowwise_residual(const Params& p, const u16* Y, const float* gpost, int mode, const u16* parts) {
;     ...
;     for (int u = 0; u < 2; u++) {
;       const int t = tb + u * stride;
;       if (t < NT) {
;         const float r = rsqrtf(ss[u] * (1.f / 1024.f) + EPS);
;         float s2 = 0.f;
; #pragma unroll
;         for (int j = 0; j < 4; j++) {
;           const float4 g = *(const float4*)(gpost + j * 256 + lane * 4);
;           float4 xn = xv[u][j];
;           xn.x += yv[u][j].x * r * g.x; xn.y += yv[u][j].y * r * g.y; xn.z += yv[u][j].z * r * g.z; xn.w += yv[u][j].w * r * g.w;
;           s2 += xn.x * xn.x + xn.y * xn.y + xn.z * xn.z + xn.w * xn.w;
;           if (mode == 2) st_nt4(y + (long)t * 1024 + j * 256 + lane * 4, xn);
;           else {
;             uint2 o; o.x = pack2(xn.x, xn.y); o.y = pack2(xn.z, xn.w);
;             *(uint2*)(xr + (long)t * XR_LD + j * 256 + lane * 4) = o;
;           }
;         }
;         if (mode != 2) {
;           s2 = wave_sum(s2);
;           if (lane == 0) rs[t] = rsqrtf(s2 * (1.f / 1024.f) + EPS);
;         }
.LBB0_1618:
	s_or_b64 exec, exec, s[2:3]
	s_and_saveexec_b64 s[2:3], s[12:13]
	s_cbranch_execz .LBB0_1609
	s_waitcnt lgkmcnt(0)
	s_nop 1
	v_mov_b32_e32 v56, v236
	v_mov_b32_e32 v57, v237
	v_mov_b32_e32 v58, v238
	v_mov_b32_e32 v59, v239
	v_mov_b32_e32 v52, v233
	v_fmamk_f32 v52, v52, 0x3a800000, v88
	v_mul_f32_e32 v53, 0x4b800000, v52
	v_cmp_gt_f32_e64 s[12:13], s30, v52
	s_nop 1
	v_cndmask_b32_e64 v52, v52, v53, s[12:13]
	v_rsq_f32_e32 v54, v52
	v_lshlrev_b64 v[52:53], 12, v[50:51]
	v_lshl_add_u64 v[60:61], v[6:7], 0, v[52:53]
	v_mul_f32_e32 v52, 0x45800000, v54
	v_cndmask_b32_e64 v62, v54, v52, s[12:13]
	v_pk_mul_f32 v[52:53], v[22:23], v[62:63] op_sel_hi:[1,0]
	v_pk_mul_f32 v[54:55], v[24:25], v[62:63] op_sel_hi:[1,0]
	v_pk_mul_f32 v[64:65], v[30:31], v[62:63] op_sel_hi:[1,0]
	v_pk_mul_f32 v[66:67], v[32:33], v[62:63] op_sel_hi:[1,0]
	v_pk_mul_f32 v[68:69], v[40:41], v[62:63] op_sel_hi:[1,0]
	v_pk_mul_f32 v[70:71], v[38:39], v[62:63] op_sel_hi:[1,0]
	v_pk_mul_f32 v[72:73], v[18:19], v[62:63] op_sel_hi:[1,0]
	v_pk_mul_f32 v[62:63], v[20:21], v[62:63] op_sel_hi:[1,0]
	v_pk_fma_f32 v[56:57], v[52:53], v[56:57], v[28:29]
	v_pk_fma_f32 v[58:59], v[54:55], v[58:59], v[26:27]
	v_cvt_pk_bf16_f32 v52, v56, v57
	v_cvt_pk_bf16_f32 v53, v58, v59
	global_store_dwordx2 v[60:61], v[52:53], off offset:2048
	s_nop 1
	v_mov_b32_e32 v52, v240
	v_mov_b32_e32 v53, v241
	v_mov_b32_e32 v54, v242
	v_mov_b32_e32 v55, v243
	v_pk_mul_f32 v[56:57], v[56:57], v[56:57]
	v_pk_mul_f32 v[58:59], v[58:59], v[58:59]
	v_add_f32_e32 v56, v56, v57
	v_add_f32_e32 v56, v56, v58
	v_add_f32_e32 v74, v56, v59
	v_pk_fma_f32 v[64:65], v[64:65], v[52:53], v[36:37]
	v_pk_fma_f32 v[66:67], v[66:67], v[54:55], v[34:35]
	v_cvt_pk_bf16_f32 v52, v64, v65
	v_cvt_pk_bf16_f32 v53, v66, v67
	global_store_dwordx2 v[60:61], v[52:53], off offset:2560
	s_nop 1
	v_mov_b32_e32 v52, v244
	v_mov_b32_e32 v53, v245
	v_mov_b32_e32 v54, v246
	v_mov_b32_e32 v55, v247
	v_pk_mul_f32 v[56:57], v[64:65], v[64:65]
	v_pk_mul_f32 v[58:59], v[66:67], v[66:67]
	v_add_f32_e32 v56, v56, v57
	v_add_f32_e32 v56, v56, v58
	v_add_f32_e32 v56, v56, v59
	v_add_f32_e32 v64, v74, v56
	v_pk_fma_f32 v[68:69], v[68:69], v[52:53], v[44:45]
	v_pk_fma_f32 v[70:71], v[70:71], v[54:55], v[42:43]
	v_cvt_pk_bf16_f32 v52, v68, v69
	v_cvt_pk_bf16_f32 v53, v70, v71
	global_store_dwordx2 v[60:61], v[52:53], off offset:3072
	s_nop 1
	v_mov_b32_e32 v52, v248
	v_mov_b32_e32 v53, v249
	v_mov_b32_e32 v54, v250
	v_mov_b32_e32 v55, v251
	v_pk_mul_f32 v[56:57], v[68:69], v[68:69]
	v_pk_mul_f32 v[58:59], v[70:71], v[70:71]
	v_add_f32_e32 v56, v56, v57
	v_add_f32_e32 v56, v56, v58
	v_add_f32_e32 v65, v56, v59
	v_pk_fma_f32 v[56:57], v[72:73], v[52:53], v[48:49]
	v_pk_fma_f32 v[54:55], v[62:63], v[54:55], v[46:47]
	v_pk_mul_f32 v[52:53], v[56:57], v[56:57]
	v_pk_mul_f32 v[58:59], v[54:55], v[54:55]
	v_add_f32_e32 v52, v52, v53
	v_add_f32_e32 v52, v52, v58
	v_add_f32_e32 v62, v64, v65
	v_add_f32_e32 v52, v52, v59
	v_add_f32_e32 v52, v62, v52
	s_nop 1
	v_add_f32_dpp v234, v52, v52 quad_perm:[1,0,3,2] row_mask:0xf bank_mask:0xf
	s_nop 1
	v_add_f32_dpp v234, v234, v234 quad_perm:[2,3,0,1] row_mask:0xf bank_mask:0xf
	s_nop 1
	v_add_f32_dpp v234, v234, v234 row_half_mirror row_mask:0xf bank_mask:0xf
	s_nop 1
	v_add_f32_dpp v234, v234, v234 row_mirror row_mask:0xf bank_mask:0xf
	s_nop 0
	v_mov_b32_e32 v255, v234
	s_nop 1
	v_permlane16_swap_b32_e32 v234, v255
	s_nop 0
	v_add_f32_e32 v234, v234, v255
	v_mov_b32_e32 v255, v234
	s_nop 1
	v_permlane32_swap_b32_e32 v234, v255
	s_nop 0
	v_add_f32_e32 v234, v234, v255
	v_cvt_pk_bf16_f32 v56, v56, v57
	v_cvt_pk_bf16_f32 v57, v54, v55
	global_store_dwordx2 v[60:61], v[56:57], off offset:3584
	s_waitcnt lgkmcnt(0)
	s_waitcnt lgkmcnt(0)
	s_waitcnt lgkmcnt(0)
	s_waitcnt lgkmcnt(0)
	s_waitcnt lgkmcnt(0)
	s_and_b64 exec, exec, s[6:7]
	s_cbranch_execz .LBB0_1609
	s_waitcnt lgkmcnt(0)
	v_mov_b32_e32 v52, v234
	v_fmamk_f32 v52, v52, 0x3a800000, v88
	v_mul_f32_e32 v53, 0x4b800000, v52
	v_cmp_gt_f32_e64 s[12:13], s30, v52
	v_lshl_add_u64 v[50:51], v[50:51], 2, s[16:17]
	s_nop 0
	v_cndmask_b32_e64 v52, v52, v53, s[12:13]
	v_rsq_f32_e32 v52, v52
	s_nop 0
	v_mul_f32_e32 v53, 0x45800000, v52
	v_cndmask_b32_e64 v52, v52, v53, s[12:13]
	global_store_dword v[50:51], v52, off
	s_branch .LBB0_1609

; DI float bf2f(u16 h) { return __uint_as_float(((unsigned)h) << 16); }
; DI uint2 ld_nt2u(const void* q) { const u32x2n v = __builtin_nontemporal_load((const u32x2n*)q); return make_uint2(v.x, v.y); }
; DI int opaque_tid() { int t = threadIdx.x; asm volatile("" : "+v"(t)); return t; }
; DI u16* xres_base(const Params& p) { return (u16*)(p.out + O_Y) + 1024; }
; DI void rowwise_residual(const Params& p, const u16* Y, const float* gpost, int mode, const u16* parts) {
;   const int tid = opaque_tid(), lane = tid & 63, w = tid >> 6;
;   float* y = p.out + O_Y;
;   u16* xr = xres_base(p);
;   float* rs = (float*)(p.ws + W_RS);
;   const int stride = gridDim.x * 4;
;   for (int tb = blockIdx.x * 4 + w; tb < NT; tb += 2 * stride) {
;     float4 yv[2][4], xv[2][4];
;     float ss[2] = {0.f, 0.f};
; #pragma unroll
;     for (int u = 0; u < 2; u++) {
;       const int t = tb + u * stride;
;       if (t < NT) {
; #pragma unroll
;         for (int j = 0; j < 4; j++) {
;           const uint2 yr = ld_nt2u(Y + (long)t * 1024 + j * 256 + lane * 4);
;           yv[u][j] = make_float4(bf2f((u16)(yr.x & 0xffff)), bf2f((u16)(yr.x >> 16)), bf2f((u16)(yr.y & 0xffff)), bf2f((u16)(yr.y >> 16)));
;           if (mode == 0) xv[u][j] = *(const float4*)(xrow(p, t) + j * 256 + lane * 4);
;     ...
;           const float4 g = *(const float4*)(gpost + j * 256 + lane * 4);
.LBB0_1817:
	s_or_b64 exec, exec, s[0:1]
	s_waitcnt lgkmcnt(0)
	s_barrier
	s_movk_i32 s8, 0x4800
	v_ashrrev_i32_e32 v0, 6, v202
	v_add_u32_e32 v52, s65, v0
	v_cmp_gt_i32_e32 vcc, s8, v52
	s_and_saveexec_b64 s[0:1], vcc
	s_cbranch_execz .LBB0_1828
	s_load_dwordx2 s[2:3], s[62:63], 0x58
	s_load_dwordx2 s[0:1], s[62:63], 0xd8
	v_and_b32_e32 v8, 63, v202
	v_lshlrev_b32_e32 v0, 3, v8
	v_mov_b32_e32 v1, 0
	v_and_b32_e32 v9, 64, v203
	v_lshl_add_u64 v[6:7], s[48:49], 0, v[0:1]
	s_mov_b64 s[4:5], 0x2800000
	s_waitcnt lgkmcnt(0)
	v_lshl_add_u64 v[4:5], s[0:1], 0, v[0:1]
	s_mov_b64 s[0:1], 0x11000000
	v_add_u32_e32 v9, 64, v9
	v_xor_b32_e32 v10, 32, v203
	v_lshl_add_u64 v[2:3], v[6:7], 0, s[4:5]
	v_lshl_add_u64 v[6:7], v[6:7], 0, s[0:1]
	v_cmp_lt_i32_e64 s[0:1], v10, v9
	v_cmp_lt_u32_e32 vcc, 31, v8
	v_lshlrev_b32_e32 v8, 4, v8
	v_cndmask_b32_e64 v10, v203, v10, s[0:1]
	s_waitcnt vmcnt(8)
	v_lshlrev_b32_e32 v76, 2, v10
	v_xor_b32_e32 v10, 16, v203
	v_cmp_lt_i32_e64 s[0:1], v10, v9
	s_mov_b64 s[4:5], 0
	s_movk_i32 s9, 0x7ff
	v_cndmask_b32_e64 v10, v203, v10, s[0:1]
	v_lshlrev_b32_e32 v77, 2, v10
	v_xor_b32_e32 v10, 8, v203
	v_cmp_lt_i32_e64 s[0:1], v10, v9
	v_mov_b32_e32 v82, 0x358637bd
	s_mov_b32 s10, 0x800000
	v_cndmask_b32_e64 v10, v203, v10, s[0:1]
	v_lshlrev_b32_e32 v78, 2, v10
	v_xor_b32_e32 v10, 4, v203
	v_cmp_lt_i32_e64 s[0:1], v10, v9
	s_movk_i32 s11, 0x47ff
	s_nop 0
	v_cndmask_b32_e64 v10, v203, v10, s[0:1]
	v_lshlrev_b32_e32 v79, 2, v10
	v_xor_b32_e32 v10, 2, v203
	v_cmp_lt_i32_e64 s[0:1], v10, v9
	s_nop 1
	v_cndmask_b32_e64 v10, v203, v10, s[0:1]
	v_lshlrev_b32_e32 v80, 2, v10
	v_xor_b32_e32 v10, 1, v203
	v_cmp_lt_i32_e64 s[0:1], v10, v9
	s_nop 1
	v_cndmask_b32_e64 v9, v203, v10, s[0:1]
	v_lshlrev_b32_e32 v81, 2, v9
	v_mov_b32_e32 v9, v1
	v_lshl_add_u64 v[8:9], s[2:3], 0, v[8:9]
	s_mov_b64 s[0:1], 0x1000
	v_lshl_add_u64 v[8:9], v[8:9], 0, s[0:1]
	global_load_dwordx4 v[236:239], v[8:9], off
	global_load_dwordx4 v[240:243], v[8:9], off offset:1024
	global_load_dwordx4 v[244:247], v[8:9], off offset:2048
	global_load_dwordx4 v[248:251], v[8:9], off offset:3072
	s_waitcnt vmcnt(0)
	v_lshl_add_u64 v[10:11], v[4:5], 0, v[0:1]
	s_branch .LBB0_1820

; DI unsigned pack2(float a, float b) { f32v2_t v = {a, b}; return __builtin_bit_cast(unsigned, __builtin_convertvector(v, bf16v2_t)); }
; DI void st_nt4(float* q, float4 v) { f32x4n t = {v.x, v.y, v.z, v.w}; __builtin_nontemporal_store(t, (f32x4n*)q); }
; DI void rowwise_residual(const Params& p, const u16* Y, const float* gpost, int mode, const u16* parts) {
;     ...
;     ss[0] = wave_sum(ss[0]); ss[1] = wave_sum(ss[1]);
; #pragma unroll
;     for (int u = 0; u < 2; u++) {
;       const int t = tb + u * stride;
;       if (t < NT) {
;         const float r = rsqrtf(ss[u] * (1.f / 1024.f) + EPS);
;         float s2 = 0.f;
; #pragma unroll
;         for (int j = 0; j < 4; j++) {
;           const float4 g = *(const float4*)(gpost + j * 256 + lane * 4);
;           float4 xn = xv[u][j];
;           xn.x += yv[u][j].x * r * g.x; xn.y += yv[u][j].y * r * g.y; xn.z += yv[u][j].z * r * g.z; xn.w += yv[u][j].w * r * g.w;
;           s2 += xn.x * xn.x + xn.y * xn.y + xn.z * xn.z + xn.w * xn.w;
;           if (mode == 2) st_nt4(y + (long)t * 1024 + j * 256 + lane * 4, xn);
;           else {
;             uint2 o; o.x = pack2(xn.x, xn.y); o.y = pack2(xn.z, xn.w);
;             *(uint2*)(xr + (long)t * XR_LD + j * 256 + lane * 4) = o;
;           }
;         }
.LBB0_1826:
	s_or_b64 exec, exec, s[6:7]
	s_nop 1
	v_mov_b32_e32 v84, v236
	v_mov_b32_e32 v85, v237
	v_mov_b32_e32 v86, v238
	v_mov_b32_e32 v87, v239
	s_nop 1
	v_add_f32_dpp v235, v72, v72 quad_perm:[1,0,3,2] row_mask:0xf bank_mask:0xf
	s_nop 1
	v_add_f32_dpp v235, v235, v235 quad_perm:[2,3,0,1] row_mask:0xf bank_mask:0xf
	s_nop 1
	v_add_f32_dpp v235, v235, v235 row_half_mirror row_mask:0xf bank_mask:0xf
	s_nop 1
	v_add_f32_dpp v235, v235, v235 row_mirror row_mask:0xf bank_mask:0xf
	s_nop 0
	v_mov_b32_e32 v255, v235
	s_nop 1
	v_permlane16_swap_b32_e32 v235, v255
	s_nop 0
	v_add_f32_e32 v235, v235, v255
	v_mov_b32_e32 v255, v235
	s_nop 1
	v_permlane32_swap_b32_e32 v235, v255
	s_nop 0
	v_add_f32_e32 v235, v235, v255
	v_lshl_add_u64 v[88:89], v[10:11], 0, v[56:57]
	v_mov_b32_e32 v56, v66
	v_mov_b32_e32 v90, v68
	v_mov_b32_e32 v91, v70
	s_waitcnt lgkmcnt(0)
	s_waitcnt vmcnt(0)
	v_and_b32_e32 v73, 0xffff0000, v58
	v_mov_b32_e32 v70, v69
	s_waitcnt lgkmcnt(0)
	s_waitcnt lgkmcnt(0)
	s_waitcnt lgkmcnt(0)
	v_lshlrev_b32_e32 v72, 16, v58
	v_lshlrev_b32_e32 v58, 16, v59
	v_and_b32_e32 v59, 0xffff0000, v59
	s_waitcnt lgkmcnt(0)
	s_waitcnt lgkmcnt(0)
	v_mov_b32_e32 v0, v235
	v_fmamk_f32 v0, v0, 0x3a800000, v82
	v_mul_f32_e32 v57, 0x4b800000, v0
	v_cmp_gt_f32_e64 s[2:3], s10, v0
	s_nop 1
	v_cndmask_b32_e64 v0, v0, v57, s[2:3]
	v_rsq_f32_e32 v0, v0
	v_mov_b32_e32 v57, v64
	v_mul_f32_e32 v64, 0x45800000, v0
	v_cndmask_b32_e64 v66, v0, v64, s[2:3]
	v_pk_mul_f32 v[56:57], v[66:67], v[56:57] op_sel_hi:[0,1]
	v_pk_mul_f32 v[90:91], v[66:67], v[90:91] op_sel_hi:[0,1]
	v_mov_b32_e32 v64, v67
	v_pk_mul_f32 v[62:63], v[66:67], v[62:63] op_sel_hi:[0,1]
	v_pk_mul_f32 v[60:61], v[66:67], v[60:61] op_sel_hi:[0,1]
	ds_bpermute_b32 v0, v76, v75
	v_pk_mul_f32 v[48:49], v[48:49], v[66:67] op_sel_hi:[1,0]
	v_pk_mul_f32 v[46:47], v[46:47], v[66:67] op_sel_hi:[1,0]
	s_waitcnt lgkmcnt(0)
	v_add_f32_e32 v0, v75, v0
	v_pk_fma_f32 v[56:57], v[84:85], v[56:57], v[72:73]
	v_pk_fma_f32 v[58:59], v[86:87], v[90:91], v[58:59]
	global_store_dwordx4 v[88:89], v[56:59], off nt
	s_nop 1
	v_mov_b32_e32 v56, v240
	v_mov_b32_e32 v57, v241
	v_mov_b32_e32 v58, v242
	v_mov_b32_e32 v59, v243
	v_lshlrev_b32_e32 v72, 16, v54
	v_and_b32_e32 v73, 0xffff0000, v54
	v_lshlrev_b32_e32 v84, 16, v55
	v_and_b32_e32 v85, 0xffff0000, v55
	v_pk_mul_f32 v[54:55], v[66:67], v[64:65] op_sel_hi:[0,1]
	v_pk_mul_f32 v[64:65], v[66:67], v[70:71] op_sel_hi:[0,1]
	v_pk_fma_f32 v[54:55], v[54:55], v[56:57], v[72:73]
	v_pk_fma_f32 v[56:57], v[64:65], v[58:59], v[84:85]
	global_store_dwordx4 v[88:89], v[54:57], off offset:1024 nt
	s_nop 1
	v_mov_b32_e32 v54, v244
	v_mov_b32_e32 v55, v245
	v_mov_b32_e32 v56, v246
	v_mov_b32_e32 v57, v247
	v_lshlrev_b32_e32 v58, 16, v50
	v_and_b32_e32 v59, 0xffff0000, v50
	v_lshlrev_b32_e32 v50, 16, v51
	v_and_b32_e32 v51, 0xffff0000, v51
	v_pk_fma_f32 v[54:55], v[60:61], v[54:55], v[58:59]
	v_pk_fma_f32 v[56:57], v[62:63], v[56:57], v[50:51]
	global_store_dwordx4 v[88:89], v[54:57], off offset:2048 nt
	s_nop 1
	v_mov_b32_e32 v54, v248
	v_mov_b32_e32 v55, v249
	v_mov_b32_e32 v56, v250
	v_mov_b32_e32 v57, v251
	ds_bpermute_b32 v50, v77, v0
	v_and_b32_e32 v51, 0xffff0000, v44
	v_lshlrev_b32_e32 v58, 16, v45
	v_and_b32_e32 v59, 0xffff0000, v45
	s_waitcnt lgkmcnt(0)
	v_add_f32_e32 v0, v0, v50
	ds_bpermute_b32 v50, v78, v0
	s_waitcnt lgkmcnt(0)
	v_add_f32_e32 v0, v0, v50
	ds_bpermute_b32 v50, v79, v0
	s_waitcnt lgkmcnt(0)
	v_add_f32_e32 v0, v0, v50
	ds_bpermute_b32 v60, v80, v0
	v_lshlrev_b32_e32 v50, 16, v44
	s_waitcnt lgkmcnt(0)
	v_add_f32_e32 v0, v0, v60
	ds_bpermute_b32 v44, v81, v0
	v_pk_fma_f32 v[46:47], v[46:47], v[54:55], v[50:51]
	v_pk_fma_f32 v[48:49], v[48:49], v[56:57], v[58:59]
	global_store_dwordx4 v[88:89], v[46:49], off offset:3072 nt
	s_and_saveexec_b64 s[2:3], s[0:1]
	s_cbranch_execz .LBB0_1819
	s_nop 1
	v_mov_b32_e32 v46, v236
	v_mov_b32_e32 v47, v237
	v_mov_b32_e32 v48, v238
	v_mov_b32_e32 v49, v239
	s_waitcnt lgkmcnt(0)
	v_add_f32_e32 v0, v0, v44
	v_fmamk_f32 v0, v0, 0x3a800000, v82
	v_mul_f32_e32 v44, 0x4b800000, v0
	v_cmp_gt_f32_e64 s[0:1], s10, v0
	s_nop 1
	v_cndmask_b32_e64 v0, v0, v44, s[0:1]
	v_rsq_f32_e32 v0, v0
	v_lshlrev_b64 v[44:45], 12, v[52:53]
	v_lshl_add_u64 v[50:51], v[10:11], 0, v[44:45]
	v_mul_f32_e32 v44, 0x45800000, v0
	v_cndmask_b32_e64 v0, v0, v44, s[0:1]
	v_pk_mul_f32 v[44:45], v[16:17], v[0:1] op_sel_hi:[1,0]
	v_pk_mul_f32 v[54:55], v[18:19], v[0:1] op_sel_hi:[1,0]
	v_pk_fma_f32 v[46:47], v[44:45], v[46:47], v[20:21]
	v_pk_fma_f32 v[48:49], v[54:55], v[48:49], v[22:23]
	global_store_dwordx4 v[50:51], v[46:49], off nt
	s_nop 1
	v_mov_b32_e32 v44, v240
	v_mov_b32_e32 v45, v241
	v_mov_b32_e32 v46, v242
	v_mov_b32_e32 v47, v243
	v_pk_mul_f32 v[54:55], v[24:25], v[0:1] op_sel_hi:[1,0]
	v_pk_mul_f32 v[48:49], v[26:27], v[0:1] op_sel_hi:[1,0]
	v_pk_fma_f32 v[44:45], v[54:55], v[44:45], v[28:29]
	v_pk_fma_f32 v[46:47], v[48:49], v[46:47], v[30:31]
	global_store_dwordx4 v[50:51], v[44:47], off offset:1024 nt
	s_nop 1
	v_mov_b32_e32 v44, v244
	v_mov_b32_e32 v45, v245
	v_mov_b32_e32 v46, v246
	v_mov_b32_e32 v47, v247
	v_pk_mul_f32 v[48:49], v[34:35], v[0:1] op_sel_hi:[1,0]
	v_pk_mul_f32 v[54:55], v[32:33], v[0:1] op_sel_hi:[1,0]
	v_pk_fma_f32 v[46:47], v[48:49], v[46:47], v[38:39]
	v_pk_fma_f32 v[44:45], v[54:55], v[44:45], v[36:37]
	global_store_dwordx4 v[50:51], v[44:47], off offset:2048 nt
	s_nop 1
	v_mov_b32_e32 v44, v248
	v_mov_b32_e32 v45, v249
	v_mov_b32_e32 v46, v250
	v_mov_b32_e32 v47, v251
	v_pk_mul_f32 v[48:49], v[14:15], v[0:1] op_sel_hi:[1,0]
	v_pk_mul_f32 v[54:55], v[12:13], v[0:1] op_sel_hi:[1,0]
	v_pk_fma_f32 v[46:47], v[48:49], v[46:47], v[42:43]
	v_pk_fma_f32 v[44:45], v[54:55], v[44:45], v[40:41]
	global_store_dwordx4 v[50:51], v[44:47], off offset:3072 nt
	s_branch .LBB0_1819
